# EpiGU: per-row rstd values cached in 16 KB spare LDS across consecutive tiles with the same row block (skips ssq loads + reduction + rsqrt on ~80% of GU tiles)
# baseline (speedup 1.0000x reference)
; __device__ __forceinline__ int tid_fresh() { int t = threadIdx.x; asm volatile("" : "+v"(t)); return t; }
; #define PG8_STAGE(bufoff, gbase, voff) do { _Pragma("unroll") for (int _i = 0; _i < 2; ++_i) \
;         __builtin_amdgcn_global_load_lds((const unsigned*)((const char*)(gbase) + (voff)[_i]), (PG8_LAS unsigned*)(lds + (bufoff) + ldsw + _i * 8192), 16, 0, 0); } while (0)
; #define PG8_BAR __builtin_amdgcn_s_barrier()
; template <class Epi, class Sched, bool ALIGN_EPI = false, bool SP2 = false>
; __device__ __forceinline__ void gemm_phase(PG8_LAS unsigned char* lds, const Gemm g, const Sched& S, const Epi& E) {
;     const int tid = tid_fresh(), wid = __builtin_amdgcn_readfirstlane(tid >> 6), lane = tid & 63, wr = wid >> 2, wc = wid & 3, fr = lane & 15, fq = lane >> 4;
;     const int K = g.K, nt = K / BK;
;     unsigned voffA[2], voffB[2];
; #pragma unroll
;     for (int i = 0; i < 2; ++i) { int R, C; stage_rc(tid * 16 + i * 8192, R, C); const int Rb = Epi::PERM ? ((R & ~31) + perm32(R & 31)) : R;
;         voffA[i] = (unsigned)(R * K + C) * 2u; voffB[i] = (unsigned)(Rb * K + C) * 2u; }
;     const size_t kstep = (size_t)(BK * 2);
;     const size_t hstep = (size_t)HALF * K * 2;
;     const size_t tstep = 2 * hstep;
;     const unsigned ldsw = (unsigned)wid * 1024u;
;     const int aoff = lds_byte(wr * 64 + fr, fq * 8), boff = lds_byte(wc * 32 + fr, fq * 8);
;     ...
;     Unit cur, nxt; int ui = 0;
;     if (!S.next(0, cur)) return;
;     f32x4 acc[2][2][4][2];
; #pragma unroll
;     for (int a = 0; a < 2; ++a)
; #pragma unroll
;         for (int b = 0; b < 2; ++b)
; #pragma unroll
;             for (int m = 0; m < 4; ++m)
; #pragma unroll
;                 for (int n = 0; n < 2; ++n) acc[a][b][m][n] = (f32x4){0.f, 0.f, 0.f, 0.f};
;     bf16x8 At[4][2], B0[2][2], B1[2][2];
;     const char* cA = (const char*)g.A + (size_t)cur.pm * tstep; const char* cB = (const char*)g.Bt + (size_t)cur.pn * tstep;
;     S.a_ready(cur);
;     if constexpr (SP2) {
;         PG8_STAGE(PG8_SB(0, 0), cB, voffB); PG8_STAGE(PG8_SB(0, 1), cB + hstep, voffB); PG8_STAGE(PG8_SA(0, 0), cA, voffA); PG8_STAGE(PG8_SA(0, 1), cA + hstep, voffA);
;         if (wr == 1) PG8_BAR;
.Lxb0_355:
	s_or_b64 exec, exec, s[46:47]
	s_mov_b64 s[6:7], s[0:1]
	s_waitcnt lgkmcnt(0)
	s_barrier
	s_movk_i32 s8, 0x400
	v_mov_b64_e32 v[2:3], s[6:7]
	flat_load_dwordx2 v[0:1], v[2:3] offset:240
	flat_load_dwordx2 v[128:129], v[2:3] offset:296
	flat_load_dwordx2 v[130:131], v[2:3] offset:216
	flat_load_dwordx2 v[132:133], v[2:3] offset:200
	s_movk_i32 s6, 0x1600
	s_mov_b32 s100, -1
	s_ashr_i32 s7, s6, 31
	s_lshr_b32 s7, s7, 24
	s_add_i32 s6, s6, s7
	s_ashr_i32 s12, s6, 8
	s_lshl_b32 s6, s12, 7
	v_mov_b32_e32 v14, v254
	s_cmp_ge_i32 s2, s6
	v_readfirstlane_b32 s7, v14
	s_cbranch_scc1 .LBB0_311
	v_lshlrev_b32_e32 v2, 4, v14
	v_add_u32_e32 v3, 0x2000, v2
	v_ashrrev_i32_e32 v4, 31, v3
	v_lshrrev_b32_e32 v4, 22, v4
	v_add_u32_e32 v4, v3, v4
	v_ashrrev_i32_e32 v4, 10, v4
	v_mul_i32_i24_e32 v5, 0x400, v4
	v_sub_u32_e32 v3, v3, v5
	v_lshrrev_b32_e32 v5, 4, v3
	v_bitop3_b32 v3, v5, v3, 32 bitop3:0x6c
	v_ashrrev_i32_e32 v5, 31, v3
	v_lshrrev_b32_e32 v5, 26, v5
	v_add_u32_e32 v5, v3, v5
	v_lshlrev_b32_e32 v7, 3, v4
	v_ashrrev_i32_e32 v6, 6, v5
	v_and_b32_e32 v7, -16, v7
	v_lshlrev_b32_e32 v4, 5, v4
	v_add_u32_e32 v7, v6, v7
	v_and_b32_e32 v15, 32, v4
	v_and_b32_e32 v4, 0xc0, v5
	v_and_b32_e32 v6, 3, v6
	s_mov_b32 s13, 0x7fffffe0
	v_lshrrev_b32_e32 v8, 2, v7
	v_lshlrev_b32_e32 v9, 1, v7
	v_sub_u32_e32 v3, v3, v4
	v_mov_b32_e32 v4, 1
	v_and_or_b32 v6, v7, s13, v6
	v_and_b32_e32 v8, 4, v8
	v_and_b32_e32 v9, 24, v9
	v_ashrrev_i16_sdwa v3, v4, sext(v3) dst_sel:DWORD dst_unused:UNUSED_PAD src0_sel:DWORD src1_sel:BYTE_0
	v_or3_b32 v6, v6, v8, v9
	v_bfe_i32 v16, v3, 0, 16
	v_mul_lo_u32 v6, v6, s8
	v_add_u32_e32 v3, v15, v16
	v_mul_lo_u32 v17, v7, s8
	v_add_lshl_u32 v134, v6, v3, 1
	v_add_lshl_u32 v136, v3, v17, 1
	v_bfe_i32 v3, v14, 27, 1
	v_lshrrev_b32_e32 v3, 22, v3
	v_add_u32_e32 v3, v2, v3
	v_and_b32_e32 v3, 0xfffffc00, v3
	v_sub_u32_e32 v2, v2, v3
	v_ashrrev_i32_e32 v5, 31, v14
	v_lshrrev_b32_e32 v3, 4, v2
	v_lshrrev_b32_e32 v5, 26, v5
	v_bitop3_b32 v3, v3, v2, 32 bitop3:0x6c
	v_ashrrev_i32_e32 v2, 31, v2
	v_add_u32_e32 v5, v14, v5
	v_lshrrev_b32_e32 v2, 26, v2
	v_ashrrev_i32_e32 v5, 6, v5
	v_add_u32_e32 v2, v3, v2
	v_lshlrev_b32_e32 v6, 3, v5
	v_ashrrev_i32_e32 v2, 6, v2
	v_and_b32_e32 v6, -16, v6
	v_add_u32_e32 v6, v2, v6
	v_and_b32_e32 v7, 3, v2
	v_and_or_b32 v7, v6, s13, v7
	s_lshr_b32 s13, s3, 29
	s_add_i32 s13, s2, s13
	s_ashr_i32 s10, s7, 6
	s_ashr_i32 s9, s8, 31
	s_lshl_b32 s31, s12, 4
	s_ashr_i32 s18, s13, 3
	s_and_b32 s13, s13, -8
	s_ashr_i32 s11, s7, 8
	s_lshl_b64 s[14:15], s[8:9], 8
	s_lshl_b64 s[16:17], s[8:9], 9
	s_lshl_b32 s29, s10, 10
	s_sub_i32 s13, s2, s13
	s_or_b32 s34, s31, 1
	s_cmp_lt_i32 s13, 0
	s_cselect_b32 s19, s34, s31
	s_lshl_b32 s35, s12, 3
	v_mul_i32_i24_e32 v2, 64, v2
	s_abs_i32 s36, s35
	v_sub_u32_e32 v2, v3, v2
	v_cvt_f32_u32_e32 v3, s36
	s_mul_i32 s13, s19, s13
	s_sub_i32 s19, 0, s36
	s_add_i32 s13, s13, s18
	v_rcp_iflag_f32_e32 v3, v3
	s_ashr_i32 s18, s13, 31
	s_bfe_i32 s37, s12, 0x1001c
	s_xor_b32 s12, s18, s37
	v_mul_f32_e32 v3, 0x4f7ffffe, v3
	v_cvt_u32_f32_e32 v3, v3
	s_abs_i32 s18, s13
	v_lshrrev_b32_e32 v8, 2, v6
	v_lshlrev_b32_e32 v9, 1, v6
	v_readfirstlane_b32 s41, v3
	s_mul_i32 s19, s19, s41
	s_mul_hi_u32 s19, s41, s19
	s_add_i32 s41, s41, s19
	s_mul_hi_u32 s19, s18, s41
	s_mul_i32 s20, s19, s36
	s_sub_i32 s18, s18, s20
	s_add_i32 s20, s19, 1
	s_sub_i32 s21, s18, s36
	s_cmp_ge_u32 s18, s36
	s_cselect_b32 s19, s20, s19
	s_cselect_b32 s18, s21, s18
	s_add_i32 s20, s19, 1
	s_cmp_ge_u32 s18, s36
	s_cselect_b32 s18, s20, s19
	s_xor_b32 s18, s18, s12
	s_sub_i32 s12, s18, s12
	s_lshl_b32 s18, s12, 3
	s_sub_i32 s19, 0x80, s18
	s_min_i32 s19, s19, 8
	s_abs_i32 s20, s19
	v_cvt_f32_u32_e32 v3, s20
	v_and_b32_e32 v8, 4, v8
	v_and_b32_e32 v9, 24, v9
	v_lshlrev_b32_e32 v5, 5, v5
	v_ashrrev_i16_sdwa v2, v4, sext(v2) dst_sel:DWORD dst_unused:UNUSED_PAD src0_sel:DWORD src1_sel:BYTE_0
	v_or3_b32 v7, v7, v8, v9
	v_and_b32_e32 v18, 32, v5
	v_bfe_i32 v19, v2, 0, 16
	v_mul_lo_u32 v7, v7, s8
	v_add_u32_e32 v2, v18, v19
	v_mul_lo_u32 v20, v6, s8
	v_add_lshl_u32 v138, v7, v2, 1
	v_add_lshl_u32 v140, v2, v20, 1
	v_rcp_iflag_f32_e32 v2, v3
	s_sub_i32 s22, 0, s20
	s_mul_i32 s12, s12, s35
	s_sub_i32 s12, s13, s12
	v_mul_f32_e32 v2, 0x4f7ffffe, v2
	v_cvt_u32_f32_e32 v2, v2
	s_abs_i32 s21, s12
	s_xor_b32 s13, s12, s19
	s_ashr_i32 s13, s13, 31
	v_readfirstlane_b32 s23, v2
	s_mul_i32 s22, s22, s23
	s_mul_hi_u32 s22, s23, s22
	s_add_i32 s23, s23, s22
	s_mul_hi_u32 s22, s21, s23
	s_mul_i32 s23, s22, s20
	s_sub_i32 s21, s21, s23
	s_add_i32 s23, s22, 1
	s_sub_i32 s24, s21, s20
	s_cmp_ge_u32 s21, s20
	s_cselect_b32 s22, s23, s22
	s_cselect_b32 s21, s24, s21
	s_add_i32 s23, s22, 1
	s_cmp_ge_u32 s21, s20
	s_cselect_b32 s20, s23, s22
	s_xor_b32 s20, s20, s13
	s_sub_i32 s66, s20, s13
	s_mul_i32 s13, s66, s19
	s_sub_i32 s12, s12, s13
	s_add_i32 s12, s12, s18
	s_ashr_i32 s18, s66, 31
	s_mul_i32 s20, s16, s18
	s_lshr_b64 s[18:19], s[8:9], 23
	s_mul_i32 s19, s18, s66
	v_mov_b32_e32 v2, s66
	s_add_i32 s19, s20, s19
	s_waitcnt vmcnt(0) lgkmcnt(0)
	v_mad_u64_u32 v[158:159], s[20:21], s16, v2, v[128:129]
	v_mov_b32_e32 v143, 0
	v_add_u32_e32 v159, s19, v159
	s_add_i32 s46, s29, 0
	v_mov_b32_e32 v139, v143
	s_ashr_i32 s13, s12, 31
	s_add_i32 m0, s46, 0x10000
	v_lshl_add_u64 v[6:7], v[158:159], 0, v[138:139]
	v_mov_b32_e32 v135, v143
	global_load_lds_dwordx4 v[6:7], off
	v_lshl_add_u64 v[8:9], v[158:159], 0, v[134:135]
	s_add_i32 m0, s46, 0x12000
	v_lshl_add_u64 v[4:5], v[158:159], 0, s[14:15]
	s_mul_i32 s13, s16, s13
	s_mul_i32 s18, s18, s12
	v_mov_b32_e32 v10, s12
	global_load_lds_dwordx4 v[8:9], off
	s_add_i32 m0, s46, 0x14000
	v_lshl_add_u64 v[2:3], v[4:5], 0, v[138:139]
	s_add_i32 s13, s13, s18
	v_mad_u64_u32 v[160:161], s[18:19], s16, v10, v[132:133]
	global_load_lds_dwordx4 v[2:3], off
	v_lshl_add_u64 v[4:5], v[4:5], 0, v[134:135]
	s_add_i32 m0, s46, 0x16000
	v_add_u32_e32 v161, s13, v161
	v_mov_b32_e32 v141, v143
	global_load_lds_dwordx4 v[4:5], off
	v_lshl_add_u64 v[10:11], v[160:161], 0, v[140:141]
	s_mov_b32 m0, s46
	v_mov_b32_e32 v137, v143
	s_add_i32 s47, s46, 0x2000
	global_load_lds_dwordx4 v[10:11], off
	v_lshl_add_u64 v[12:13], v[160:161], 0, v[136:137]
	s_mov_b32 m0, s47
	v_lshl_add_u64 v[22:23], v[160:161], 0, s[14:15]
	s_add_i32 s48, s46, 0x4000
	global_load_lds_dwordx4 v[12:13], off
	v_lshl_add_u64 v[24:25], v[22:23], 0, v[140:141]
	s_mov_b32 m0, s48
	s_add_i32 s49, s46, 0x6000
	global_load_lds_dwordx4 v[24:25], off
	v_lshl_add_u64 v[22:23], v[22:23], 0, v[136:137]
	s_mov_b32 m0, s49
	s_cmp_eq_u32 s11, 1
	global_load_lds_dwordx4 v[22:23], off
	s_cselect_b64 s[18:19], -1, 0
	s_cmp_lg_u32 s11, 1
	s_mov_b32 s21, 0
	s_cbranch_scc1 .LBB0_293
	s_barrier

; #define GAS __attribute__((address_space(1)))
; template <int NP>
; __device__ __forceinline__ void rows_rstd(const float* ssq, float invn, const Unit& u, int wr, int fr, int fq, float (&rs)[2][4]) {
; #pragma unroll
;   for (int ai = 0; ai < 2; ++ai)
; #pragma unroll
;     for (int m = 0; m < 4; ++m) {
;       const int row = erow(u, ai, wr, m, fr);
;       float s;
;       if (NP == 16) {
;         const f32x4 v = *(GAS const f32x4*)(ssq + (size_t)row * 16 + 4 * fq);
;         s = (v[0] + v[1]) + (v[2] + v[3]);
;         s += __shfl_xor(s, 16); s += __shfl_xor(s, 32);
;       } else {
;         const f32x4 v = *(GAS const f32x4*)(ssq + (size_t)row * 4);
;         s = (v[0] + v[1]) + (v[2] + v[3]);
;       }
;       rs[ai][m] = rsqrtf(s * invn + RMS_EPS);
;     }
;   __device__ __forceinline__ void operator()(ACC_T, const Unit& u, int wr, int wc, int fr, int fq) const {
;     float rs[2][4]; rows_rstd<16>(ssq, 1.0f / DM, u, wr, fr, fq, rs);
.LBB0_307:
	s_lshl_b32 s67, s12, 8
	s_cmp_eq_u32 s100, s12
	s_cbranch_scc1 .Lrsc_hit_0
	v_add_u32_e32 v172, s67, v167
	v_ashrrev_i32_e32 v173, 31, v172
	v_or_b32_e32 v160, 16, v172
	v_lshlrev_b64 v[158:159], 6, v[172:173]
	v_ashrrev_i32_e32 v161, 31, v160
	v_lshl_add_u64 v[158:159], v[144:145], 0, v[158:159]
	v_lshlrev_b64 v[160:161], 6, v[160:161]
	v_lshl_add_u64 v[160:161], v[144:145], 0, v[160:161]
	global_load_dwordx4 v[182:185], v[158:159], off
	global_load_dwordx4 v[186:189], v[160:161], off
	v_or_b32_e32 v158, 32, v172
	v_ashrrev_i32_e32 v159, 31, v158
	v_lshlrev_b64 v[158:159], 6, v[158:159]
	v_lshl_add_u64 v[158:159], v[144:145], 0, v[158:159]
	global_load_dwordx4 v[190:193], v[158:159], off
	v_or_b32_e32 v158, 48, v172
	v_ashrrev_i32_e32 v159, 31, v158
	v_lshlrev_b64 v[158:159], 6, v[158:159]
	v_lshl_add_u64 v[158:159], v[144:145], 0, v[158:159]
	global_load_dwordx4 v[194:197], v[158:159], off
	v_add_u32_e32 v164, 0x80, v172
	v_ashrrev_i32_e32 v165, 31, v164
	v_lshlrev_b64 v[158:159], 6, v[164:165]
	v_add_u32_e32 v162, 0x90, v172
	v_lshl_add_u64 v[158:159], v[144:145], 0, v[158:159]
	v_ashrrev_i32_e32 v163, 31, v162
	global_load_dwordx4 v[198:201], v[158:159], off
	v_lshlrev_b64 v[158:159], 6, v[162:163]
	v_lshl_add_u64 v[158:159], v[144:145], 0, v[158:159]
	global_load_dwordx4 v[202:205], v[158:159], off
	v_and_b32_e32 v159, 64, v180
	v_xor_b32_e32 v158, 16, v180
	v_add_u32_e32 v159, 64, v159
	v_xor_b32_e32 v160, 32, v180
	v_cmp_lt_i32_e32 vcc, v158, v159
	v_mov_b64_e32 v[214:215], s[30:31]
	s_nop 0
	v_cndmask_b32_e32 v161, v180, v158, vcc
	v_cmp_lt_i32_e32 vcc, v160, v159
	v_add_u32_e32 v158, 0xb0, v172
	v_lshlrev_b32_e32 v163, 2, v161
	v_cndmask_b32_e32 v159, v180, v160, vcc
	v_add_u32_e32 v160, 0xa0, v172
	v_lshlrev_b32_e32 v165, 2, v159
	v_ashrrev_i32_e32 v161, 31, v160
	v_ashrrev_i32_e32 v159, 31, v158
	v_lshlrev_b64 v[170:171], 6, v[160:161]
	v_lshlrev_b64 v[206:207], 6, v[158:159]
	v_lshl_add_u64 v[170:171], v[144:145], 0, v[170:171]
	v_lshl_add_u64 v[210:211], v[144:145], 0, v[206:207]
	global_load_dwordx4 v[206:209], v[170:171], off
	s_nop 0
	global_load_dwordx4 v[210:213], v[210:211], off
	s_waitcnt vmcnt(0)
	v_mov_b32_e32 v170, v183
	v_mov_b32_e32 v171, v184
	v_mov_b32_e32 v183, v185
	v_pk_add_f32 v[170:171], v[170:171], v[182:183]
	v_mov_b32_e32 v182, v187
	v_mov_b32_e32 v183, v188
	v_mov_b32_e32 v187, v189
	v_mov_b32_e32 v184, v191
	v_mov_b32_e32 v185, v192
	v_mov_b32_e32 v191, v193
	v_pk_add_f32 v[182:183], v[182:183], v[186:187]
	v_mov_b32_e32 v188, v195
	v_mov_b32_e32 v189, v196
	v_mov_b32_e32 v195, v197
	v_mov_b32_e32 v187, v170
	v_pk_add_f32 v[184:185], v[184:185], v[190:191]
	v_pk_add_f32 v[188:189], v[188:189], v[194:195]
	v_mov_b32_e32 v186, v182
	v_mov_b32_e32 v170, v183
	v_mov_b32_e32 v182, v188
	v_mov_b32_e32 v183, v184
	v_mov_b32_e32 v184, v189
	v_pk_add_f32 v[170:171], v[186:187], v[170:171]
	v_pk_add_f32 v[182:183], v[182:183], v[184:185]
	ds_bpermute_b32 v185, v163, v171
	ds_bpermute_b32 v184, v163, v170
	ds_bpermute_b32 v187, v163, v183
	ds_bpermute_b32 v186, v163, v182
	v_mov_b32_e32 v188, v199
	v_mov_b32_e32 v189, v200
	s_waitcnt lgkmcnt(0)
	v_pk_add_f32 v[170:171], v[170:171], v[184:185]
	ds_bpermute_b32 v185, v165, v171
	ds_bpermute_b32 v184, v165, v170
	v_pk_add_f32 v[182:183], v[182:183], v[186:187]
	ds_bpermute_b32 v187, v165, v183
	ds_bpermute_b32 v186, v165, v182
	v_mov_b32_e32 v199, v201
	s_waitcnt lgkmcnt(2)
	v_pk_add_f32 v[170:171], v[170:171], v[184:185]
	v_mov_b32_e32 v190, v203
	v_pk_fma_f32 v[170:171], v[170:171], s[28:29], v[214:215] op_sel_hi:[1,0,0]
	v_mov_b32_e32 v191, v204
	v_mul_f32_e32 v159, 0x4b800000, v171
	v_mul_f32_e32 v161, 0x4b800000, v170
	v_cmp_gt_f32_e32 vcc, s58, v171
	v_cmp_gt_f32_e64 s[10:11], s58, v170
	v_mov_b32_e32 v203, v205
	v_pk_add_f32 v[188:189], v[188:189], v[198:199]
	v_cndmask_b32_e32 v159, v171, v159, vcc
	v_cndmask_b32_e64 v161, v170, v161, s[10:11]
	v_pk_add_f32 v[170:171], v[190:191], v[202:203]
	s_waitcnt lgkmcnt(0)
	v_pk_add_f32 v[182:183], v[182:183], v[186:187]
	v_mov_b32_e32 v186, v170
	v_mov_b32_e32 v187, v188
	v_mov_b32_e32 v188, v171
	v_pk_add_f32 v[170:171], v[186:187], v[188:189]
	v_rsq_f32_e32 v159, v159
	ds_bpermute_b32 v187, v163, v171
	ds_bpermute_b32 v186, v163, v170
	v_pk_fma_f32 v[182:183], v[182:183], s[28:29], v[214:215] op_sel_hi:[1,0,0]
	v_mul_f32_e32 v168, 0x45800000, v159
	v_mul_f32_e32 v166, 0x4b800000, v183
	v_cmp_gt_f32_e64 s[12:13], s58, v183
	v_cndmask_b32_e32 v184, v159, v168, vcc
	v_mul_f32_e32 v159, 0x4b800000, v182
	v_cmp_gt_f32_e32 vcc, s58, v182
	s_waitcnt lgkmcnt(0)
	v_pk_add_f32 v[170:171], v[170:171], v[186:187]
	v_cndmask_b32_e64 v166, v183, v166, s[12:13]
	v_cndmask_b32_e32 v159, v182, v159, vcc
	ds_bpermute_b32 v183, v165, v171
	ds_bpermute_b32 v182, v165, v170
	v_mov_b32_e32 v186, v211
	v_mov_b32_e32 v187, v212
	v_mov_b32_e32 v211, v213
	v_pk_add_f32 v[186:187], v[186:187], v[210:211]
	s_waitcnt lgkmcnt(0)
	v_pk_add_f32 v[170:171], v[170:171], v[182:183]
	v_mov_b32_e32 v182, v207
	v_mov_b32_e32 v183, v208
	v_mov_b32_e32 v207, v209
	v_pk_add_f32 v[182:183], v[182:183], v[206:207]
	v_mov_b32_e32 v188, v186
	v_mov_b32_e32 v189, v182
	v_mov_b32_e32 v182, v187
	v_pk_add_f32 v[182:183], v[188:189], v[182:183]
	ds_bpermute_b32 v187, v163, v183
	ds_bpermute_b32 v186, v163, v182
	v_rsq_f32_e32 v161, v161
	v_rsq_f32_e32 v166, v166
	v_pk_fma_f32 v[170:171], v[170:171], s[28:29], v[214:215] op_sel_hi:[1,0,0]
	v_rsq_f32_e32 v159, v159
	v_mul_f32_e32 v173, 0x45800000, v161
	s_waitcnt lgkmcnt(0)
; #define GAS __attribute__((address_space(1)))
; __device__ __forceinline__ float sigmoidf_fast(float z) { return fast_rcp(1.f + fast_exp2(-z * LOG2E)); }
; template <int NP>
; __device__ __forceinline__ void rows_rstd(const float* ssq, float invn, const Unit& u, int wr, int fr, int fq, float (&rs)[2][4]) {
;     ...
;       rs[ai][m] = rsqrtf(s * invn + RMS_EPS);
;     }
;   __device__ __forceinline__ void operator()(ACC_T, const Unit& u, int wr, int wc, int fr, int fq) const {
;     float rs[2][4]; rows_rstd<16>(ssq, 1.0f / DM, u, wr, fr, fq, rs);
; #pragma unroll
;     for (int ai = 0; ai < 2; ++ai)
; #pragma unroll
;       for (int m = 0; m < 4; ++m) {
;         const int row = erow(u, ai, wr, m, fr); const float r = rs[ai][m];
;         float v[8];
; #pragma unroll
;         for (int n = 0; n < 2; ++n)
; #pragma unroll
;           for (int j = 0; j < 4; ++j) {
;             const float g = acc[ai][0][m][n][j] * r, uu = acc[ai][1][m][n][j] * r;
;             v[4 * n + j] = g * sigmoidf_fast(g) * uu;
;           }
;         u32x4 w; w.x = pk_bf16(v[0], v[1]); w.y = pk_bf16(v[2], v[3]); w.z = pk_bf16(v[4], v[5]); w.w = pk_bf16(v[6], v[7]);
;         *(GAS u32x4*)(act + (size_t)row * DFF + 128 * u.pn + 32 * wc + 8 * fq) = w;
	v_pk_add_f32 v[182:183], v[182:183], v[186:187]
	v_cndmask_b32_e64 v178, v161, v173, s[10:11]
	v_mul_f32_e32 v161, 0x45800000, v166
	ds_bpermute_b32 v187, v165, v183
	ds_bpermute_b32 v186, v165, v182
	v_cndmask_b32_e64 v176, v166, v161, s[12:13]
	v_mul_f32_e32 v166, 0x4b800000, v171
	v_cmp_gt_f32_e64 s[10:11], s58, v171
	v_mul_f32_e32 v161, 0x45800000, v159
	s_waitcnt lgkmcnt(0)
	v_pk_add_f32 v[182:183], v[182:183], v[186:187]
	v_cndmask_b32_e64 v166, v171, v166, s[10:11]
	v_rsq_f32_e32 v166, v166
	v_mul_f32_e32 v163, 0x4b800000, v170
	v_cmp_gt_f32_e64 s[12:13], s58, v170
	v_pk_fma_f32 v[182:183], v[182:183], s[28:29], v[214:215] op_sel_hi:[1,0,0]
	v_cndmask_b32_e32 v174, v159, v161, vcc
	v_cndmask_b32_e64 v163, v170, v163, s[12:13]
	v_mul_f32_e32 v159, 0x45800000, v166
	v_mul_f32_e32 v161, 0x4b800000, v183
	v_cmp_gt_f32_e32 vcc, s58, v183
	v_rsq_f32_e32 v163, v163
	v_cndmask_b32_e64 v170, v166, v159, s[10:11]
	v_cndmask_b32_e32 v161, v183, v161, vcc
	v_mul_f32_e32 v165, 0x4b800000, v182
	v_cmp_gt_f32_e64 s[10:11], s58, v182
	v_rsq_f32_e32 v161, v161
	v_mul_f32_e32 v159, 0x45800000, v163
	v_cndmask_b32_e64 v165, v182, v165, s[10:11]
	v_rsq_f32_e32 v165, v165
	v_cndmask_b32_e64 v168, v163, v159, s[12:13]
	v_mul_f32_e32 v159, 0x45800000, v161
	v_cndmask_b32_e32 v166, v161, v159, vcc
	v_mul_f32_e32 v159, 0x45800000, v165
	v_cndmask_b32_e64 v186, v165, v159, s[10:11]
	v_lshlrev_b32_e32 v255, 2, v254
	v_add_u32_e32 v255, 0x20010, v255
	ds_write_b32 v255, v184
	ds_write_b32 v255, v178 offset:2048
	ds_write_b32 v255, v176 offset:4096
	ds_write_b32 v255, v174 offset:6144
	ds_write_b32 v255, v170 offset:8192
	ds_write_b32 v255, v168 offset:10240
	ds_write_b32 v255, v166 offset:12288
	ds_write_b32 v255, v186 offset:14336
	s_mov_b32 s100, s12
	s_branch .Lrsc_join_0
.Lrsc_hit_0:
	v_add_u32_e32 v172, s67, v167
	v_lshlrev_b32_e32 v255, 2, v254
	v_add_u32_e32 v255, 0x20010, v255
	ds_read_b32 v184, v255
	ds_read_b32 v178, v255 offset:2048
	ds_read_b32 v176, v255 offset:4096
	ds_read_b32 v174, v255 offset:6144
	ds_read_b32 v170, v255 offset:8192
	ds_read_b32 v168, v255 offset:10240
	ds_read_b32 v166, v255 offset:12288
	ds_read_b32 v186, v255 offset:14336
	v_add_u32_e32 v164, 0x80, v172
	v_add_u32_e32 v162, 0x90, v172
	v_add_u32_e32 v160, 0xa0, v172
	v_add_u32_e32 v158, 0xb0, v172
	s_waitcnt lgkmcnt(0)
.Lrsc_join_0:
	v_pk_mul_f32 v[182:183], v[124:125], v[184:185] op_sel_hi:[1,0]
	v_mul_f32_e32 v124, 0xbfb8aa3b, v182
	v_exp_f32_e32 v125, v124
	v_mov_b32_e32 v124, v186
	v_mul_f32_e32 v159, 0xbfb8aa3b, v183
	v_exp_f32_e32 v159, v159
	v_add_f32_e32 v125, 1.0, v125
	v_pk_mul_f32 v[126:127], v[126:127], v[184:185] op_sel_hi:[1,0]
	v_rcp_f32_e32 v186, v125
	v_add_f32_e32 v125, 1.0, v159
	v_mul_f32_e32 v159, 0xbfb8aa3b, v126
	v_exp_f32_e32 v159, v159
	v_mul_f32_e32 v161, 0xbfb8aa3b, v127
	v_exp_f32_e32 v161, v161
	v_rcp_f32_e32 v187, v125
	v_add_f32_e32 v125, 1.0, v159
	v_rcp_f32_e32 v188, v125
	v_add_f32_e32 v125, 1.0, v161
	v_rcp_f32_e32 v189, v125
	v_pk_mul_f32 v[116:117], v[116:117], v[184:185] op_sel_hi:[1,0]
	v_pk_mul_f32 v[122:123], v[122:123], v[184:185] op_sel_hi:[1,0]
	v_mul_f32_e32 v125, 0xbfb8aa3b, v116
	v_pk_mul_f32 v[126:127], v[126:127], v[188:189]
	v_exp_f32_e32 v125, v125
	v_pk_mul_f32 v[122:123], v[122:123], v[126:127]
	v_mul_f32_e32 v126, 0xbfb8aa3b, v117
	v_exp_f32_e32 v127, v126
	v_add_f32_e32 v125, 1.0, v125
	v_pk_mul_f32 v[118:119], v[118:119], v[184:185] op_sel_hi:[1,0]
	v_rcp_f32_e32 v126, v125
	v_add_f32_e32 v125, 1.0, v127
	v_mul_f32_e32 v127, 0xbfb8aa3b, v118
	v_exp_f32_e32 v159, v127
	v_mul_f32_e32 v127, 0xbfb8aa3b, v119
	v_exp_f32_e32 v161, v127
	v_pk_mul_f32 v[120:121], v[120:121], v[184:185] op_sel_hi:[1,0]
	v_pk_mul_f32 v[182:183], v[182:183], v[186:187]
	v_rcp_f32_e32 v127, v125
	v_add_f32_e32 v125, 1.0, v159
	v_pk_mul_f32 v[120:121], v[120:121], v[182:183]
	v_rcp_f32_e32 v182, v125
	v_add_f32_e32 v125, 1.0, v161
	v_rcp_f32_e32 v183, v125
	v_pk_mul_f32 v[112:113], v[112:113], v[184:185] op_sel_hi:[1,0]
	v_pk_mul_f32 v[116:117], v[116:117], v[126:127]
	v_pk_mul_f32 v[108:109], v[108:109], v[178:179] op_sel_hi:[1,0]
	v_pk_mul_f32 v[116:117], v[112:113], v[116:117]
	v_pk_mul_f32 v[112:113], v[114:115], v[184:185] op_sel_hi:[1,0]
	v_pk_mul_f32 v[114:115], v[118:119], v[182:183]
	v_pk_mul_f32 v[110:111], v[110:111], v[178:179] op_sel_hi:[1,0]
	v_pk_mul_f32 v[118:119], v[112:113], v[114:115]
	v_cvt_pk_bf16_f32 v114, v116, v117
	v_mad_i64_i32 v[116:117], s[10:11], v172, s59, v[130:131]
	s_lshl_b32 s10, s66, 7
	s_ashr_i32 s11, s10, 31
	s_lshl_b64 s[10:11], s[10:11], 1
	v_lshl_add_u64 v[116:117], v[116:117], 0, s[10:11]
	v_lshl_add_u64 v[116:117], v[116:117], 0, s[20:21]
	v_cvt_pk_bf16_f32 v112, v120, v121
	v_cvt_pk_bf16_f32 v113, v122, v123
	v_cvt_pk_bf16_f32 v115, v118, v119
	v_lshl_add_u64 v[116:117], v[116:117], 0, v[142:143]
	global_store_dwordx4 v[116:117], v[112:115], off
	v_pk_mul_f32 v[104:105], v[104:105], v[178:179] op_sel_hi:[1,0]
	v_pk_mul_f32 v[100:101], v[100:101], v[178:179] op_sel_hi:[1,0]
	v_mul_f32_e32 v112, 0xbfb8aa3b, v108
	v_mul_f32_e32 v113, 0xbfb8aa3b, v109
	v_exp_f32_e32 v112, v112
	v_exp_f32_e32 v113, v113
	v_mul_f32_e32 v114, 0xbfb8aa3b, v110
	v_mul_f32_e32 v115, 0xbfb8aa3b, v111
	v_exp_f32_e32 v114, v114
	v_exp_f32_e32 v115, v115
	v_add_f32_e32 v112, 1.0, v112
	v_add_f32_e32 v113, 1.0, v113
	v_rcp_f32_e32 v112, v112
	v_rcp_f32_e32 v113, v113
	v_add_f32_e32 v114, 1.0, v114
	v_add_f32_e32 v115, 1.0, v115
	v_rcp_f32_e32 v114, v114
	v_rcp_f32_e32 v115, v115
	v_pk_mul_f32 v[108:109], v[108:109], v[112:113]
	v_pk_mul_f32 v[106:107], v[106:107], v[178:179] op_sel_hi:[1,0]
	v_pk_mul_f32 v[104:105], v[104:105], v[108:109]
; #define GAS __attribute__((address_space(1)))
; __device__ __forceinline__ float sigmoidf_fast(float z) { return fast_rcp(1.f + fast_exp2(-z * LOG2E)); }
; #define ROW_FENCE() asm volatile("" ::: "memory")
;   __device__ __forceinline__ void operator()(ACC_T, const Unit& u, int wr, int wc, int fr, int fq) const {
;     ...
;     for (int ai = 0; ai < 2; ++ai)
; #pragma unroll
;       for (int m = 0; m < 4; ++m) {
;         const int row = erow(u, ai, wr, m, fr); const float r = rs[ai][m];
;         float v[8];
; #pragma unroll
;         for (int n = 0; n < 2; ++n)
; #pragma unroll
;           for (int j = 0; j < 4; ++j) {
;             const float g = acc[ai][0][m][n][j] * r, uu = acc[ai][1][m][n][j] * r;
;             v[4 * n + j] = g * sigmoidf_fast(g) * uu;
;           }
;         u32x4 w; w.x = pk_bf16(v[0], v[1]); w.y = pk_bf16(v[2], v[3]); w.z = pk_bf16(v[4], v[5]); w.w = pk_bf16(v[6], v[7]);
;         *(GAS u32x4*)(act + (size_t)row * DFF + 128 * u.pn + 32 * wc + 8 * fq) = w;
;         ROW_FENCE();
	v_pk_mul_f32 v[108:109], v[110:111], v[114:115]
	v_mul_f32_e32 v110, 0xbfb8aa3b, v100
	v_exp_f32_e32 v110, v110
	v_pk_mul_f32 v[106:107], v[106:107], v[108:109]
	v_mul_f32_e32 v108, 0xbfb8aa3b, v101
	v_pk_mul_f32 v[102:103], v[102:103], v[178:179] op_sel_hi:[1,0]
	v_exp_f32_e32 v109, v108
	v_add_f32_e32 v108, 1.0, v110
	v_mul_f32_e32 v110, 0xbfb8aa3b, v102
	v_mul_f32_e32 v111, 0xbfb8aa3b, v103
	v_exp_f32_e32 v110, v110
	v_exp_f32_e32 v111, v111
	v_add_f32_e32 v109, 1.0, v109
	v_rcp_f32_e32 v108, v108
	v_rcp_f32_e32 v109, v109
	v_add_f32_e32 v110, 1.0, v110
	v_add_f32_e32 v111, 1.0, v111
	v_rcp_f32_e32 v110, v110
	v_rcp_f32_e32 v111, v111
	v_pk_mul_f32 v[96:97], v[96:97], v[178:179] op_sel_hi:[1,0]
	v_pk_mul_f32 v[100:101], v[100:101], v[108:109]
	v_add_u32_e32 v108, s67, v181
	v_pk_mul_f32 v[100:101], v[96:97], v[100:101]
	v_pk_mul_f32 v[96:97], v[98:99], v[178:179] op_sel_hi:[1,0]
	v_pk_mul_f32 v[98:99], v[102:103], v[110:111]
	v_pk_mul_f32 v[92:93], v[92:93], v[176:177] op_sel_hi:[1,0]
	v_pk_mul_f32 v[102:103], v[96:97], v[98:99]
	v_cvt_pk_bf16_f32 v98, v100, v101
	v_mad_i64_i32 v[100:101], s[12:13], v108, s59, v[130:131]
	v_lshl_add_u64 v[100:101], v[100:101], 0, s[10:11]
	v_lshl_add_u64 v[100:101], v[100:101], 0, s[20:21]
	v_cvt_pk_bf16_f32 v96, v104, v105
	v_cvt_pk_bf16_f32 v97, v106, v107
	v_cvt_pk_bf16_f32 v99, v102, v103
	v_lshl_add_u64 v[100:101], v[100:101], 0, v[142:143]
	global_store_dwordx4 v[100:101], v[96:99], off
	v_pk_mul_f32 v[94:95], v[94:95], v[176:177] op_sel_hi:[1,0]
	v_pk_mul_f32 v[88:89], v[88:89], v[176:177] op_sel_hi:[1,0]
	v_mul_f32_e32 v96, 0xbfb8aa3b, v92
	v_mul_f32_e32 v97, 0xbfb8aa3b, v93
	v_exp_f32_e32 v96, v96
	v_exp_f32_e32 v97, v97
	v_mul_f32_e32 v98, 0xbfb8aa3b, v94
	v_mul_f32_e32 v99, 0xbfb8aa3b, v95
	v_exp_f32_e32 v98, v98
	v_exp_f32_e32 v99, v99
	v_add_f32_e32 v96, 1.0, v96
	v_add_f32_e32 v97, 1.0, v97
	v_rcp_f32_e32 v96, v96
	v_rcp_f32_e32 v97, v97
	v_add_f32_e32 v98, 1.0, v98
	v_add_f32_e32 v99, 1.0, v99
	v_rcp_f32_e32 v98, v98
	v_rcp_f32_e32 v99, v99
	v_pk_mul_f32 v[92:93], v[92:93], v[96:97]
	v_pk_mul_f32 v[84:85], v[84:85], v[176:177] op_sel_hi:[1,0]
	v_pk_mul_f32 v[88:89], v[88:89], v[92:93]
	v_pk_mul_f32 v[92:93], v[94:95], v[98:99]
	v_mul_f32_e32 v94, 0xbfb8aa3b, v84
	v_exp_f32_e32 v94, v94
	v_pk_mul_f32 v[90:91], v[90:91], v[176:177] op_sel_hi:[1,0]
	v_pk_mul_f32 v[86:87], v[86:87], v[176:177] op_sel_hi:[1,0]
	v_pk_mul_f32 v[90:91], v[90:91], v[92:93]
	v_mul_f32_e32 v92, 0xbfb8aa3b, v85
	v_exp_f32_e32 v93, v92
	v_add_f32_e32 v92, 1.0, v94
	v_mul_f32_e32 v94, 0xbfb8aa3b, v86
	v_mul_f32_e32 v95, 0xbfb8aa3b, v87
	v_exp_f32_e32 v94, v94
	v_exp_f32_e32 v95, v95
	v_add_f32_e32 v93, 1.0, v93
	v_rcp_f32_e32 v92, v92
	v_rcp_f32_e32 v93, v93
	v_add_f32_e32 v94, 1.0, v94
	v_add_f32_e32 v95, 1.0, v95
	v_rcp_f32_e32 v94, v94
	v_rcp_f32_e32 v95, v95
	v_pk_mul_f32 v[80:81], v[80:81], v[176:177] op_sel_hi:[1,0]
	v_pk_mul_f32 v[84:85], v[84:85], v[92:93]
	v_add_u32_e32 v92, s67, v175
	v_pk_mul_f32 v[84:85], v[80:81], v[84:85]
	v_pk_mul_f32 v[80:81], v[82:83], v[176:177] op_sel_hi:[1,0]
	v_pk_mul_f32 v[82:83], v[86:87], v[94:95]
	v_pk_mul_f32 v[76:77], v[76:77], v[174:175] op_sel_hi:[1,0]
	v_pk_mul_f32 v[86:87], v[80:81], v[82:83]
	v_cvt_pk_bf16_f32 v82, v84, v85
	v_mad_i64_i32 v[84:85], s[12:13], v92, s59, v[130:131]
	v_lshl_add_u64 v[84:85], v[84:85], 0, s[10:11]
	v_lshl_add_u64 v[84:85], v[84:85], 0, s[20:21]
	v_cvt_pk_bf16_f32 v80, v88, v89
	v_cvt_pk_bf16_f32 v81, v90, v91
	v_cvt_pk_bf16_f32 v83, v86, v87
	v_lshl_add_u64 v[84:85], v[84:85], 0, v[142:143]
	global_store_dwordx4 v[84:85], v[80:83], off
	v_pk_mul_f32 v[78:79], v[78:79], v[174:175] op_sel_hi:[1,0]
	v_pk_mul_f32 v[72:73], v[72:73], v[174:175] op_sel_hi:[1,0]
	v_mul_f32_e32 v80, 0xbfb8aa3b, v76
	v_mul_f32_e32 v81, 0xbfb8aa3b, v77
	v_exp_f32_e32 v80, v80
	v_exp_f32_e32 v81, v81
	v_mul_f32_e32 v82, 0xbfb8aa3b, v78
	v_mul_f32_e32 v83, 0xbfb8aa3b, v79
	v_exp_f32_e32 v82, v82
	v_exp_f32_e32 v83, v83
	v_add_f32_e32 v80, 1.0, v80
	v_add_f32_e32 v81, 1.0, v81
	v_rcp_f32_e32 v80, v80
	v_rcp_f32_e32 v81, v81
	v_add_f32_e32 v82, 1.0, v82
	v_add_f32_e32 v83, 1.0, v83
	v_rcp_f32_e32 v82, v82
	v_rcp_f32_e32 v83, v83
	v_pk_mul_f32 v[76:77], v[76:77], v[80:81]
	v_pk_mul_f32 v[68:69], v[68:69], v[174:175] op_sel_hi:[1,0]
	v_pk_mul_f32 v[72:73], v[72:73], v[76:77]
	v_pk_mul_f32 v[76:77], v[78:79], v[82:83]
	v_mul_f32_e32 v78, 0xbfb8aa3b, v68
	v_exp_f32_e32 v78, v78
	v_pk_mul_f32 v[74:75], v[74:75], v[174:175] op_sel_hi:[1,0]
	v_pk_mul_f32 v[70:71], v[70:71], v[174:175] op_sel_hi:[1,0]
	v_pk_mul_f32 v[74:75], v[74:75], v[76:77]
	v_mul_f32_e32 v76, 0xbfb8aa3b, v69
	v_exp_f32_e32 v77, v76
	v_add_f32_e32 v76, 1.0, v78
	v_mul_f32_e32 v78, 0xbfb8aa3b, v70
	v_mul_f32_e32 v79, 0xbfb8aa3b, v71
	v_exp_f32_e32 v78, v78
	v_exp_f32_e32 v79, v79
	v_add_f32_e32 v77, 1.0, v77
	v_rcp_f32_e32 v76, v76
	v_rcp_f32_e32 v77, v77
	v_add_f32_e32 v78, 1.0, v78
	v_add_f32_e32 v79, 1.0, v79
	v_rcp_f32_e32 v78, v78
	v_rcp_f32_e32 v79, v79
	v_pk_mul_f32 v[64:65], v[64:65], v[174:175] op_sel_hi:[1,0]
	v_pk_mul_f32 v[68:69], v[68:69], v[76:77]
	v_add_u32_e32 v76, s67, v177
	v_pk_mul_f32 v[68:69], v[64:65], v[68:69]
	v_pk_mul_f32 v[64:65], v[66:67], v[174:175] op_sel_hi:[1,0]
	v_pk_mul_f32 v[66:67], v[70:71], v[78:79]
	v_pk_mul_f32 v[60:61], v[60:61], v[170:171] op_sel_hi:[1,0]
	v_pk_mul_f32 v[70:71], v[64:65], v[66:67]
	v_cvt_pk_bf16_f32 v66, v68, v69
	v_mad_i64_i32 v[68:69], s[12:13], v76, s59, v[130:131]
	v_lshl_add_u64 v[68:69], v[68:69], 0, s[10:11]
	v_lshl_add_u64 v[68:69], v[68:69], 0, s[20:21]
	v_cvt_pk_bf16_f32 v64, v72, v73
	v_cvt_pk_bf16_f32 v65, v74, v75
	v_cvt_pk_bf16_f32 v67, v70, v71
; #define GAS __attribute__((address_space(1)))
; __device__ __forceinline__ float sigmoidf_fast(float z) { return fast_rcp(1.f + fast_exp2(-z * LOG2E)); }
; #define ROW_FENCE() asm volatile("" ::: "memory")
;   __device__ __forceinline__ void operator()(ACC_T, const Unit& u, int wr, int wc, int fr, int fq) const {
;     ...
;     for (int ai = 0; ai < 2; ++ai)
; #pragma unroll
;       for (int m = 0; m < 4; ++m) {
;         const int row = erow(u, ai, wr, m, fr); const float r = rs[ai][m];
;         float v[8];
; #pragma unroll
;         for (int n = 0; n < 2; ++n)
; #pragma unroll
;           for (int j = 0; j < 4; ++j) {
;             const float g = acc[ai][0][m][n][j] * r, uu = acc[ai][1][m][n][j] * r;
;             v[4 * n + j] = g * sigmoidf_fast(g) * uu;
;           }
;         u32x4 w; w.x = pk_bf16(v[0], v[1]); w.y = pk_bf16(v[2], v[3]); w.z = pk_bf16(v[4], v[5]); w.w = pk_bf16(v[6], v[7]);
;         *(GAS u32x4*)(act + (size_t)row * DFF + 128 * u.pn + 32 * wc + 8 * fq) = w;
;         ROW_FENCE();
	v_lshl_add_u64 v[68:69], v[68:69], 0, v[142:143]
	global_store_dwordx4 v[68:69], v[64:67], off
	v_pk_mul_f32 v[62:63], v[62:63], v[170:171] op_sel_hi:[1,0]
	v_pk_mul_f32 v[56:57], v[56:57], v[170:171] op_sel_hi:[1,0]
	v_mul_f32_e32 v64, 0xbfb8aa3b, v60
	v_mul_f32_e32 v65, 0xbfb8aa3b, v61
	v_exp_f32_e32 v64, v64
	v_exp_f32_e32 v65, v65
	v_mul_f32_e32 v66, 0xbfb8aa3b, v62
	v_mul_f32_e32 v67, 0xbfb8aa3b, v63
	v_exp_f32_e32 v66, v66
	v_exp_f32_e32 v67, v67
	v_add_f32_e32 v64, 1.0, v64
	v_add_f32_e32 v65, 1.0, v65
	v_rcp_f32_e32 v64, v64
	v_rcp_f32_e32 v65, v65
	v_add_f32_e32 v66, 1.0, v66
	v_add_f32_e32 v67, 1.0, v67
	v_rcp_f32_e32 v66, v66
	v_rcp_f32_e32 v67, v67
	v_pk_mul_f32 v[60:61], v[60:61], v[64:65]
	v_pk_mul_f32 v[52:53], v[52:53], v[170:171] op_sel_hi:[1,0]
	v_pk_mul_f32 v[56:57], v[56:57], v[60:61]
	v_pk_mul_f32 v[60:61], v[62:63], v[66:67]
	v_mul_f32_e32 v62, 0xbfb8aa3b, v52
	v_exp_f32_e32 v62, v62
	v_pk_mul_f32 v[58:59], v[58:59], v[170:171] op_sel_hi:[1,0]
	v_pk_mul_f32 v[54:55], v[54:55], v[170:171] op_sel_hi:[1,0]
	v_pk_mul_f32 v[58:59], v[58:59], v[60:61]
	v_mul_f32_e32 v60, 0xbfb8aa3b, v53
	v_exp_f32_e32 v61, v60
	v_add_f32_e32 v60, 1.0, v62
	v_mul_f32_e32 v62, 0xbfb8aa3b, v54
	v_mul_f32_e32 v63, 0xbfb8aa3b, v55
	v_exp_f32_e32 v62, v62
	v_exp_f32_e32 v63, v63
	v_add_f32_e32 v61, 1.0, v61
	v_rcp_f32_e32 v60, v60
	v_rcp_f32_e32 v61, v61
	v_add_f32_e32 v62, 1.0, v62
	v_add_f32_e32 v63, 1.0, v63
	v_rcp_f32_e32 v62, v62
	v_rcp_f32_e32 v63, v63
	v_pk_mul_f32 v[48:49], v[48:49], v[170:171] op_sel_hi:[1,0]
	v_pk_mul_f32 v[52:53], v[52:53], v[60:61]
	v_pk_mul_f32 v[44:45], v[44:45], v[168:169] op_sel_hi:[1,0]
	v_pk_mul_f32 v[52:53], v[48:49], v[52:53]
	v_pk_mul_f32 v[48:49], v[50:51], v[170:171] op_sel_hi:[1,0]
	v_pk_mul_f32 v[50:51], v[54:55], v[62:63]
	v_pk_mul_f32 v[46:47], v[46:47], v[168:169] op_sel_hi:[1,0]
	v_pk_mul_f32 v[54:55], v[48:49], v[50:51]
	v_cvt_pk_bf16_f32 v50, v52, v53
	v_mad_i64_i32 v[52:53], s[12:13], v164, s59, v[130:131]
	v_lshl_add_u64 v[52:53], v[52:53], 0, s[10:11]
	v_lshl_add_u64 v[52:53], v[52:53], 0, s[20:21]
	v_cvt_pk_bf16_f32 v48, v56, v57
	v_cvt_pk_bf16_f32 v49, v58, v59
	v_cvt_pk_bf16_f32 v51, v54, v55
	v_lshl_add_u64 v[52:53], v[52:53], 0, v[142:143]
	global_store_dwordx4 v[52:53], v[48:51], off
	v_pk_mul_f32 v[40:41], v[40:41], v[168:169] op_sel_hi:[1,0]
	v_pk_mul_f32 v[36:37], v[36:37], v[168:169] op_sel_hi:[1,0]
	v_mul_f32_e32 v48, 0xbfb8aa3b, v44
	v_mul_f32_e32 v49, 0xbfb8aa3b, v45
	v_exp_f32_e32 v48, v48
	v_exp_f32_e32 v49, v49
	v_mul_f32_e32 v50, 0xbfb8aa3b, v46
	v_mul_f32_e32 v51, 0xbfb8aa3b, v47
	v_exp_f32_e32 v50, v50
	v_exp_f32_e32 v51, v51
	v_add_f32_e32 v48, 1.0, v48
	v_add_f32_e32 v49, 1.0, v49
	v_rcp_f32_e32 v48, v48
	v_rcp_f32_e32 v49, v49
	v_add_f32_e32 v50, 1.0, v50
	v_add_f32_e32 v51, 1.0, v51
	v_rcp_f32_e32 v50, v50
	v_rcp_f32_e32 v51, v51
	v_pk_mul_f32 v[44:45], v[44:45], v[48:49]
	v_pk_mul_f32 v[42:43], v[42:43], v[168:169] op_sel_hi:[1,0]
	v_pk_mul_f32 v[40:41], v[40:41], v[44:45]
	v_pk_mul_f32 v[44:45], v[46:47], v[50:51]
	v_mul_f32_e32 v46, 0xbfb8aa3b, v36
	v_exp_f32_e32 v46, v46
	v_pk_mul_f32 v[42:43], v[42:43], v[44:45]
	v_mul_f32_e32 v44, 0xbfb8aa3b, v37
	v_pk_mul_f32 v[38:39], v[38:39], v[168:169] op_sel_hi:[1,0]
	v_exp_f32_e32 v45, v44
	v_add_f32_e32 v44, 1.0, v46
	v_mul_f32_e32 v46, 0xbfb8aa3b, v38
	v_mul_f32_e32 v47, 0xbfb8aa3b, v39
	v_exp_f32_e32 v46, v46
	v_exp_f32_e32 v47, v47
	v_add_f32_e32 v45, 1.0, v45
	v_rcp_f32_e32 v44, v44
	v_rcp_f32_e32 v45, v45
	v_add_f32_e32 v46, 1.0, v46
	v_add_f32_e32 v47, 1.0, v47
	v_rcp_f32_e32 v46, v46
	v_rcp_f32_e32 v47, v47
	v_pk_mul_f32 v[32:33], v[32:33], v[168:169] op_sel_hi:[1,0]
	v_pk_mul_f32 v[36:37], v[36:37], v[44:45]
	v_pk_mul_f32 v[28:29], v[28:29], v[166:167] op_sel_hi:[1,0]
	v_pk_mul_f32 v[36:37], v[32:33], v[36:37]
	v_pk_mul_f32 v[32:33], v[34:35], v[168:169] op_sel_hi:[1,0]
	v_pk_mul_f32 v[34:35], v[38:39], v[46:47]
	v_pk_mul_f32 v[30:31], v[30:31], v[166:167] op_sel_hi:[1,0]
	v_pk_mul_f32 v[38:39], v[32:33], v[34:35]
	v_cvt_pk_bf16_f32 v34, v36, v37
	v_mad_i64_i32 v[36:37], s[12:13], v162, s59, v[130:131]
	v_lshl_add_u64 v[36:37], v[36:37], 0, s[10:11]
	v_lshl_add_u64 v[36:37], v[36:37], 0, s[20:21]
	v_cvt_pk_bf16_f32 v32, v40, v41
	v_cvt_pk_bf16_f32 v33, v42, v43
	v_cvt_pk_bf16_f32 v35, v38, v39
; #define PG8_BAR __builtin_amdgcn_s_barrier()
; #define GAS __attribute__((address_space(1)))
; __device__ __forceinline__ float sigmoidf_fast(float z) { return fast_rcp(1.f + fast_exp2(-z * LOG2E)); }
; #define ROW_FENCE() asm volatile("" ::: "memory")
; template <class Epi, class Sched, bool ALIGN_EPI = false, bool SP2 = false>
; __device__ __forceinline__ void gemm_phase(PG8_LAS unsigned char* lds, const Gemm g, const Sched& S, const Epi& E) {
;     ...
;         if constexpr (!Epi::AFTER_DRAIN) { E(acc, cur, wr, wc, fr, fq); S.done(cur); }
;         if (!has_next) break;
; #pragma unroll
;         for (int a = 0; a < 2; ++a)
; #pragma unroll
;             for (int b = 0; b < 2; ++b)
; #pragma unroll
;                 for (int m = 0; m < 4; ++m)
; #pragma unroll
;                     for (int n = 0; n < 2; ++n) acc[a][b][m][n] = (f32x4){0.f, 0.f, 0.f, 0.f};
;         cur = nxt; cA = nA; cB = nB; ++ui;
;         if constexpr (ALIGN_EPI) { if (wr == 1) PG8_BAR; }
;   __device__ __forceinline__ void operator()(ACC_T, const Unit& u, int wr, int wc, int fr, int fq) const {
;     ...
;     for (int ai = 0; ai < 2; ++ai)
; #pragma unroll
;       for (int m = 0; m < 4; ++m) {
;         const int row = erow(u, ai, wr, m, fr); const float r = rs[ai][m];
;         float v[8];
; #pragma unroll
;         for (int n = 0; n < 2; ++n)
; #pragma unroll
;           for (int j = 0; j < 4; ++j) {
;             const float g = acc[ai][0][m][n][j] * r, uu = acc[ai][1][m][n][j] * r;
;             v[4 * n + j] = g * sigmoidf_fast(g) * uu;
;           }
;         u32x4 w; w.x = pk_bf16(v[0], v[1]); w.y = pk_bf16(v[2], v[3]); w.z = pk_bf16(v[4], v[5]); w.w = pk_bf16(v[6], v[7]);
;         *(GAS u32x4*)(act + (size_t)row * DFF + 128 * u.pn + 32 * wc + 8 * fq) = w;
;         ROW_FENCE();
	v_lshl_add_u64 v[36:37], v[36:37], 0, v[142:143]
	global_store_dwordx4 v[36:37], v[32:35], off
	v_pk_mul_f32 v[24:25], v[24:25], v[166:167] op_sel_hi:[1,0]
	v_pk_mul_f32 v[20:21], v[20:21], v[166:167] op_sel_hi:[1,0]
	v_mul_f32_e32 v32, 0xbfb8aa3b, v28
	v_mul_f32_e32 v33, 0xbfb8aa3b, v29
	v_exp_f32_e32 v32, v32
	v_exp_f32_e32 v33, v33
	v_mul_f32_e32 v34, 0xbfb8aa3b, v30
	v_mul_f32_e32 v35, 0xbfb8aa3b, v31
	v_exp_f32_e32 v34, v34
	v_exp_f32_e32 v35, v35
	v_add_f32_e32 v32, 1.0, v32
	v_add_f32_e32 v33, 1.0, v33
	v_rcp_f32_e32 v32, v32
	v_rcp_f32_e32 v33, v33
	v_add_f32_e32 v34, 1.0, v34
	v_add_f32_e32 v35, 1.0, v35
	v_rcp_f32_e32 v34, v34
	v_rcp_f32_e32 v35, v35
	v_pk_mul_f32 v[28:29], v[28:29], v[32:33]
	v_pk_mul_f32 v[26:27], v[26:27], v[166:167] op_sel_hi:[1,0]
	v_pk_mul_f32 v[24:25], v[24:25], v[28:29]
	v_pk_mul_f32 v[28:29], v[30:31], v[34:35]
	v_mul_f32_e32 v30, 0xbfb8aa3b, v20
	v_exp_f32_e32 v30, v30
	v_pk_mul_f32 v[26:27], v[26:27], v[28:29]
	v_mul_f32_e32 v28, 0xbfb8aa3b, v21
	v_pk_mul_f32 v[22:23], v[22:23], v[166:167] op_sel_hi:[1,0]
	v_exp_f32_e32 v29, v28
	v_add_f32_e32 v28, 1.0, v30
	v_mul_f32_e32 v30, 0xbfb8aa3b, v22
	v_mul_f32_e32 v31, 0xbfb8aa3b, v23
	v_exp_f32_e32 v30, v30
	v_exp_f32_e32 v31, v31
	v_add_f32_e32 v29, 1.0, v29
	v_rcp_f32_e32 v28, v28
	v_rcp_f32_e32 v29, v29
	v_add_f32_e32 v30, 1.0, v30
	v_add_f32_e32 v31, 1.0, v31
	v_rcp_f32_e32 v30, v30
	v_rcp_f32_e32 v31, v31
	v_pk_mul_f32 v[16:17], v[16:17], v[166:167] op_sel_hi:[1,0]
	v_pk_mul_f32 v[20:21], v[20:21], v[28:29]
	v_pk_mul_f32 v[12:13], v[12:13], v[124:125] op_sel_hi:[1,0]
	v_pk_mul_f32 v[20:21], v[16:17], v[20:21]
	v_pk_mul_f32 v[16:17], v[18:19], v[166:167] op_sel_hi:[1,0]
	v_pk_mul_f32 v[18:19], v[22:23], v[30:31]
	v_pk_mul_f32 v[14:15], v[14:15], v[124:125] op_sel_hi:[1,0]
	v_pk_mul_f32 v[22:23], v[16:17], v[18:19]
	v_cvt_pk_bf16_f32 v18, v20, v21
	v_mad_i64_i32 v[20:21], s[12:13], v160, s59, v[130:131]
	v_lshl_add_u64 v[20:21], v[20:21], 0, s[10:11]
	v_lshl_add_u64 v[20:21], v[20:21], 0, s[20:21]
	v_cvt_pk_bf16_f32 v16, v24, v25
	v_cvt_pk_bf16_f32 v17, v26, v27
	v_cvt_pk_bf16_f32 v19, v22, v23
	v_lshl_add_u64 v[20:21], v[20:21], 0, v[142:143]
	global_store_dwordx4 v[20:21], v[16:19], off
	v_pk_mul_f32 v[8:9], v[8:9], v[124:125] op_sel_hi:[1,0]
	v_pk_mul_f32 v[4:5], v[4:5], v[124:125] op_sel_hi:[1,0]
	v_mul_f32_e32 v16, 0xbfb8aa3b, v12
	v_mul_f32_e32 v17, 0xbfb8aa3b, v13
	v_exp_f32_e32 v16, v16
	v_exp_f32_e32 v17, v17
	v_mul_f32_e32 v18, 0xbfb8aa3b, v14
	v_mul_f32_e32 v19, 0xbfb8aa3b, v15
	v_exp_f32_e32 v18, v18
	v_exp_f32_e32 v19, v19
	v_add_f32_e32 v16, 1.0, v16
	v_add_f32_e32 v17, 1.0, v17
	v_rcp_f32_e32 v16, v16
	v_rcp_f32_e32 v17, v17
	v_add_f32_e32 v18, 1.0, v18
	v_add_f32_e32 v19, 1.0, v19
	v_rcp_f32_e32 v18, v18
	v_rcp_f32_e32 v19, v19
	v_pk_mul_f32 v[12:13], v[12:13], v[16:17]
	v_pk_mul_f32 v[10:11], v[10:11], v[124:125] op_sel_hi:[1,0]
	v_pk_mul_f32 v[8:9], v[8:9], v[12:13]
	v_pk_mul_f32 v[12:13], v[14:15], v[18:19]
	v_mul_f32_e32 v14, 0xbfb8aa3b, v4
	v_exp_f32_e32 v14, v14
	v_pk_mul_f32 v[10:11], v[10:11], v[12:13]
	v_mul_f32_e32 v12, 0xbfb8aa3b, v5
	v_pk_mul_f32 v[6:7], v[6:7], v[124:125] op_sel_hi:[1,0]
	v_exp_f32_e32 v13, v12
	v_add_f32_e32 v12, 1.0, v14
	v_mul_f32_e32 v14, 0xbfb8aa3b, v6
	v_mul_f32_e32 v15, 0xbfb8aa3b, v7
	v_exp_f32_e32 v14, v14
	v_exp_f32_e32 v15, v15
	v_add_f32_e32 v13, 1.0, v13
	v_rcp_f32_e32 v12, v12
	v_rcp_f32_e32 v13, v13
	v_add_f32_e32 v14, 1.0, v14
	v_add_f32_e32 v15, 1.0, v15
	v_rcp_f32_e32 v14, v14
	v_rcp_f32_e32 v15, v15
	v_pk_mul_f32 v[0:1], v[0:1], v[124:125] op_sel_hi:[1,0]
	v_pk_mul_f32 v[4:5], v[4:5], v[12:13]
	s_and_b64 vcc, exec, s[8:9]
	v_pk_mul_f32 v[4:5], v[0:1], v[4:5]
	v_pk_mul_f32 v[0:1], v[2:3], v[124:125] op_sel_hi:[1,0]
	v_pk_mul_f32 v[2:3], v[6:7], v[14:15]
	s_mov_b64 s[8:9], -1
	v_pk_mul_f32 v[6:7], v[0:1], v[2:3]
	v_cvt_pk_bf16_f32 v2, v4, v5
	v_mad_i64_i32 v[4:5], s[12:13], v158, s59, v[130:131]
	v_lshl_add_u64 v[4:5], v[4:5], 0, s[10:11]
	v_lshl_add_u64 v[4:5], v[4:5], 0, s[20:21]
	v_cvt_pk_bf16_f32 v0, v8, v9
	v_cvt_pk_bf16_f32 v1, v10, v11
	v_cvt_pk_bf16_f32 v3, v6, v7
	v_lshl_add_u64 v[4:5], v[4:5], 0, v[142:143]
	global_store_dwordx4 v[4:5], v[0:3], off
	s_cbranch_vccnz .LBB0_295
	s_andn2_b64 vcc, exec, s[18:19]
	s_cbranch_vccnz .LBB0_294
	s_barrier
	s_branch .LBB0_294

; __device__ __forceinline__ int tid_fresh() { int t = threadIdx.x; asm volatile("" : "+v"(t)); return t; }
; #define PG8_STAGE(bufoff, gbase, voff) do { _Pragma("unroll") for (int _i = 0; _i < 2; ++_i) \
;         __builtin_amdgcn_global_load_lds((const unsigned*)((const char*)(gbase) + (voff)[_i]), (PG8_LAS unsigned*)(lds + (bufoff) + ldsw + _i * 8192), 16, 0, 0); } while (0)
; #define PG8_BAR __builtin_amdgcn_s_barrier()
; template <class Epi, class Sched, bool ALIGN_EPI = false, bool SP2 = false>
; __device__ __forceinline__ void gemm_phase(PG8_LAS unsigned char* lds, const Gemm g, const Sched& S, const Epi& E) {
;     const int tid = tid_fresh(), wid = __builtin_amdgcn_readfirstlane(tid >> 6), lane = tid & 63, wr = wid >> 2, wc = wid & 3, fr = lane & 15, fq = lane >> 4;
;     const int K = g.K, nt = K / BK;
;     unsigned voffA[2], voffB[2];
; #pragma unroll
;     for (int i = 0; i < 2; ++i) { int R, C; stage_rc(tid * 16 + i * 8192, R, C); const int Rb = Epi::PERM ? ((R & ~31) + perm32(R & 31)) : R;
;         voffA[i] = (unsigned)(R * K + C) * 2u; voffB[i] = (unsigned)(Rb * K + C) * 2u; }
;     const size_t kstep = (size_t)(BK * 2);
;     const size_t hstep = (size_t)HALF * K * 2;
;     const size_t tstep = 2 * hstep;
;     const unsigned ldsw = (unsigned)wid * 1024u;
;     const int aoff = lds_byte(wr * 64 + fr, fq * 8), boff = lds_byte(wc * 32 + fr, fq * 8);
;     ...
;     Unit cur, nxt; int ui = 0;
;     if (!S.next(0, cur)) return;
;     f32x4 acc[2][2][4][2];
; #pragma unroll
;     for (int a = 0; a < 2; ++a)
; #pragma unroll
;         for (int b = 0; b < 2; ++b)
; #pragma unroll
;             for (int m = 0; m < 4; ++m)
; #pragma unroll
;                 for (int n = 0; n < 2; ++n) acc[a][b][m][n] = (f32x4){0.f, 0.f, 0.f, 0.f};
;     bf16x8 At[4][2], B0[2][2], B1[2][2];
;     const char* cA = (const char*)g.A + (size_t)cur.pm * tstep; const char* cB = (const char*)g.Bt + (size_t)cur.pn * tstep;
;     S.a_ready(cur);
;     if constexpr (SP2) {
;         PG8_STAGE(PG8_SB(0, 0), cB, voffB); PG8_STAGE(PG8_SB(0, 1), cB + hstep, voffB); PG8_STAGE(PG8_SA(0, 0), cA, voffA); PG8_STAGE(PG8_SA(0, 1), cA + hstep, voffA);
;         if (wr == 1) PG8_BAR;
.LBB0_1007:
	s_or_b64 exec, exec, s[46:47]
	s_mov_b64 s[6:7], s[0:1]
	s_waitcnt lgkmcnt(0)
	s_barrier
	s_movk_i32 s8, 0x400
	v_mov_b64_e32 v[2:3], s[6:7]
	flat_load_dwordx2 v[0:1], v[2:3] offset:232
	flat_load_dwordx2 v[128:129], v[2:3] offset:312
	flat_load_dwordx2 v[130:131], v[2:3] offset:216
	flat_load_dwordx2 v[132:133], v[2:3] offset:192
	s_movk_i32 s6, 0x1600
	s_mov_b32 s100, -1
	s_ashr_i32 s7, s6, 31
	s_lshr_b32 s7, s7, 24
	s_add_i32 s6, s6, s7
	s_ashr_i32 s12, s6, 8
	s_lshl_b32 s6, s12, 7
	v_mov_b32_e32 v14, v254
	s_cmp_ge_i32 s2, s6
	v_readfirstlane_b32 s7, v14
	s_cbranch_scc1 .LBB0_1028
	v_lshlrev_b32_e32 v2, 4, v14
	v_add_u32_e32 v3, 0x2000, v2
	v_ashrrev_i32_e32 v4, 31, v3
	v_lshrrev_b32_e32 v4, 22, v4
	v_add_u32_e32 v4, v3, v4
	v_ashrrev_i32_e32 v4, 10, v4
	v_mul_i32_i24_e32 v5, 0x400, v4
	v_sub_u32_e32 v3, v3, v5
	v_lshrrev_b32_e32 v5, 4, v3
	v_bitop3_b32 v3, v5, v3, 32 bitop3:0x6c
	v_ashrrev_i32_e32 v5, 31, v3
	v_lshrrev_b32_e32 v5, 26, v5
	v_add_u32_e32 v5, v3, v5
	v_lshlrev_b32_e32 v7, 3, v4
	v_ashrrev_i32_e32 v6, 6, v5
	v_and_b32_e32 v7, -16, v7
	v_lshlrev_b32_e32 v4, 5, v4
	v_add_u32_e32 v7, v6, v7
	v_and_b32_e32 v15, 32, v4
	v_and_b32_e32 v4, 0xc0, v5
	v_and_b32_e32 v6, 3, v6
	s_mov_b32 s13, 0x7fffffe0
	v_lshrrev_b32_e32 v8, 2, v7
	v_lshlrev_b32_e32 v9, 1, v7
	v_sub_u32_e32 v3, v3, v4
	v_mov_b32_e32 v4, 1
	v_and_or_b32 v6, v7, s13, v6
	v_and_b32_e32 v8, 4, v8
	v_and_b32_e32 v9, 24, v9
	v_ashrrev_i16_sdwa v3, v4, sext(v3) dst_sel:DWORD dst_unused:UNUSED_PAD src0_sel:DWORD src1_sel:BYTE_0
	v_or3_b32 v6, v6, v8, v9
	v_bfe_i32 v16, v3, 0, 16
	v_mul_lo_u32 v6, v6, s8
	v_add_u32_e32 v3, v15, v16
	v_mul_lo_u32 v17, v7, s8
	v_add_lshl_u32 v134, v6, v3, 1
	v_add_lshl_u32 v136, v3, v17, 1
	v_bfe_i32 v3, v14, 27, 1
	v_lshrrev_b32_e32 v3, 22, v3
	v_add_u32_e32 v3, v2, v3
	v_and_b32_e32 v3, 0xfffffc00, v3
	v_sub_u32_e32 v2, v2, v3
	v_ashrrev_i32_e32 v5, 31, v14
	v_lshrrev_b32_e32 v3, 4, v2
	v_lshrrev_b32_e32 v5, 26, v5
	v_bitop3_b32 v3, v3, v2, 32 bitop3:0x6c
	v_ashrrev_i32_e32 v2, 31, v2
	v_add_u32_e32 v5, v14, v5
	v_lshrrev_b32_e32 v2, 26, v2
	v_ashrrev_i32_e32 v5, 6, v5
	v_add_u32_e32 v2, v3, v2
	v_lshlrev_b32_e32 v6, 3, v5
	v_ashrrev_i32_e32 v2, 6, v2
	v_and_b32_e32 v6, -16, v6
	v_add_u32_e32 v6, v2, v6
	v_and_b32_e32 v7, 3, v2
	v_and_or_b32 v7, v6, s13, v7
	s_lshr_b32 s13, s3, 29
	s_add_i32 s13, s2, s13
	s_ashr_i32 s10, s7, 6
	s_ashr_i32 s9, s8, 31
	s_lshl_b32 s31, s12, 4
	s_ashr_i32 s18, s13, 3
	s_and_b32 s13, s13, -8
	s_ashr_i32 s11, s7, 8
	s_lshl_b64 s[14:15], s[8:9], 8
	s_lshl_b64 s[16:17], s[8:9], 9
	s_lshl_b32 s29, s10, 10
	s_sub_i32 s13, s2, s13
	s_or_b32 s34, s31, 1
	s_cmp_lt_i32 s13, 0
	s_cselect_b32 s19, s34, s31
	s_lshl_b32 s35, s12, 3
	v_mul_i32_i24_e32 v2, 64, v2
	s_abs_i32 s36, s35
	v_sub_u32_e32 v2, v3, v2
	v_cvt_f32_u32_e32 v3, s36
	s_mul_i32 s13, s19, s13
	s_sub_i32 s19, 0, s36
	s_add_i32 s13, s13, s18
	v_rcp_iflag_f32_e32 v3, v3
	s_ashr_i32 s18, s13, 31
	s_bfe_i32 s37, s12, 0x1001c
	s_xor_b32 s12, s18, s37
	v_mul_f32_e32 v3, 0x4f7ffffe, v3
	v_cvt_u32_f32_e32 v3, v3
	s_abs_i32 s18, s13
	v_lshrrev_b32_e32 v8, 2, v6
	v_lshlrev_b32_e32 v9, 1, v6
	v_readfirstlane_b32 s41, v3
	s_mul_i32 s19, s19, s41
	s_mul_hi_u32 s19, s41, s19
	s_add_i32 s41, s41, s19
	s_mul_hi_u32 s19, s18, s41
	s_mul_i32 s20, s19, s36
	s_sub_i32 s18, s18, s20
	s_add_i32 s20, s19, 1
	s_sub_i32 s21, s18, s36
	s_cmp_ge_u32 s18, s36
	s_cselect_b32 s19, s20, s19
	s_cselect_b32 s18, s21, s18
	s_add_i32 s20, s19, 1
	s_cmp_ge_u32 s18, s36
	s_cselect_b32 s18, s20, s19
	s_xor_b32 s18, s18, s12
	s_sub_i32 s12, s18, s12
	s_lshl_b32 s18, s12, 3
	s_sub_i32 s19, 0x80, s18
	s_min_i32 s19, s19, 8
	s_abs_i32 s20, s19
	v_cvt_f32_u32_e32 v3, s20
	v_and_b32_e32 v8, 4, v8
	v_and_b32_e32 v9, 24, v9
	v_lshlrev_b32_e32 v5, 5, v5
	v_ashrrev_i16_sdwa v2, v4, sext(v2) dst_sel:DWORD dst_unused:UNUSED_PAD src0_sel:DWORD src1_sel:BYTE_0
	v_or3_b32 v7, v7, v8, v9
	v_and_b32_e32 v18, 32, v5
	v_bfe_i32 v19, v2, 0, 16
	v_mul_lo_u32 v7, v7, s8
	v_add_u32_e32 v2, v18, v19
	v_mul_lo_u32 v20, v6, s8
	v_add_lshl_u32 v138, v7, v2, 1
	v_add_lshl_u32 v140, v2, v20, 1
	v_rcp_iflag_f32_e32 v2, v3
	s_sub_i32 s22, 0, s20
	s_mul_i32 s12, s12, s35
	s_sub_i32 s12, s13, s12
	v_mul_f32_e32 v2, 0x4f7ffffe, v2
	v_cvt_u32_f32_e32 v2, v2
	s_abs_i32 s21, s12
	s_xor_b32 s13, s12, s19
	s_ashr_i32 s13, s13, 31
	v_readfirstlane_b32 s23, v2
	s_mul_i32 s22, s22, s23
	s_mul_hi_u32 s22, s23, s22
	s_add_i32 s23, s23, s22
	s_mul_hi_u32 s22, s21, s23
	s_mul_i32 s23, s22, s20
	s_sub_i32 s21, s21, s23
	s_add_i32 s23, s22, 1
	s_sub_i32 s24, s21, s20
	s_cmp_ge_u32 s21, s20
	s_cselect_b32 s22, s23, s22
	s_cselect_b32 s21, s24, s21
	s_add_i32 s23, s22, 1
	s_cmp_ge_u32 s21, s20
	s_cselect_b32 s20, s23, s22
	s_xor_b32 s20, s20, s13
	s_sub_i32 s67, s20, s13
	s_mul_i32 s13, s67, s19
	s_sub_i32 s12, s12, s13
	s_add_i32 s12, s12, s18
	s_ashr_i32 s18, s67, 31
	s_mul_i32 s20, s16, s18
	s_lshr_b64 s[18:19], s[8:9], 23
	s_mul_i32 s19, s18, s67
	v_mov_b32_e32 v2, s67
	s_add_i32 s19, s20, s19
	s_waitcnt vmcnt(0) lgkmcnt(0)
	v_mad_u64_u32 v[158:159], s[20:21], s16, v2, v[128:129]
	v_mov_b32_e32 v143, 0
	v_add_u32_e32 v159, s19, v159
	s_add_i32 s46, s29, 0
	v_mov_b32_e32 v139, v143
	s_ashr_i32 s13, s12, 31
	s_add_i32 m0, s46, 0x10000
	v_lshl_add_u64 v[6:7], v[158:159], 0, v[138:139]
	v_mov_b32_e32 v135, v143
	global_load_lds_dwordx4 v[6:7], off
	v_lshl_add_u64 v[8:9], v[158:159], 0, v[134:135]
	s_add_i32 m0, s46, 0x12000
	v_lshl_add_u64 v[4:5], v[158:159], 0, s[14:15]
	s_mul_i32 s13, s16, s13
	s_mul_i32 s18, s18, s12
	v_mov_b32_e32 v10, s12
	global_load_lds_dwordx4 v[8:9], off
	s_add_i32 m0, s46, 0x14000
	v_lshl_add_u64 v[2:3], v[4:5], 0, v[138:139]
	s_add_i32 s13, s13, s18
	v_mad_u64_u32 v[160:161], s[18:19], s16, v10, v[132:133]
	global_load_lds_dwordx4 v[2:3], off
	v_lshl_add_u64 v[4:5], v[4:5], 0, v[134:135]
	s_add_i32 m0, s46, 0x16000
	v_add_u32_e32 v161, s13, v161
	v_mov_b32_e32 v141, v143
	global_load_lds_dwordx4 v[4:5], off
	v_lshl_add_u64 v[10:11], v[160:161], 0, v[140:141]
	s_mov_b32 m0, s46
	v_mov_b32_e32 v137, v143
	s_add_i32 s47, s46, 0x2000
	global_load_lds_dwordx4 v[10:11], off
	v_lshl_add_u64 v[12:13], v[160:161], 0, v[136:137]
	s_mov_b32 m0, s47
	v_lshl_add_u64 v[22:23], v[160:161], 0, s[14:15]
	s_add_i32 s48, s46, 0x4000
	global_load_lds_dwordx4 v[12:13], off
	v_lshl_add_u64 v[24:25], v[22:23], 0, v[140:141]
	s_mov_b32 m0, s48
	s_add_i32 s49, s46, 0x6000
	global_load_lds_dwordx4 v[24:25], off
	v_lshl_add_u64 v[22:23], v[22:23], 0, v[136:137]
	s_mov_b32 m0, s49
	s_cmp_eq_u32 s11, 1
	global_load_lds_dwordx4 v[22:23], off
	s_cselect_b64 s[18:19], -1, 0
	s_cmp_lg_u32 s11, 1
	s_mov_b32 s21, 0
	s_cbranch_scc1 .LBB0_1010
	s_barrier

; #define GAS __attribute__((address_space(1)))
; template <int NP>
; __device__ __forceinline__ void rows_rstd(const float* ssq, float invn, const Unit& u, int wr, int fr, int fq, float (&rs)[2][4]) {
; #pragma unroll
;   for (int ai = 0; ai < 2; ++ai)
; #pragma unroll
;     for (int m = 0; m < 4; ++m) {
;       const int row = erow(u, ai, wr, m, fr);
;       float s;
;       if (NP == 16) {
;         const f32x4 v = *(GAS const f32x4*)(ssq + (size_t)row * 16 + 4 * fq);
;         s = (v[0] + v[1]) + (v[2] + v[3]);
;         s += __shfl_xor(s, 16); s += __shfl_xor(s, 32);
;       } else {
;         const f32x4 v = *(GAS const f32x4*)(ssq + (size_t)row * 4);
;         s = (v[0] + v[1]) + (v[2] + v[3]);
;       }
;       rs[ai][m] = rsqrtf(s * invn + RMS_EPS);
;     }
;   __device__ __forceinline__ void operator()(ACC_T, const Unit& u, int wr, int wc, int fr, int fq) const {
;     float rs[2][4]; rows_rstd<16>(ssq, 1.0f / DM, u, wr, fr, fq, rs);
.LBB0_1024:
	s_lshl_b32 s68, s12, 8
	s_cmp_eq_u32 s100, s12
	s_cbranch_scc1 .Lrsc_hit_1
	v_add_u32_e32 v172, s68, v167
	v_ashrrev_i32_e32 v173, 31, v172
	v_or_b32_e32 v160, 16, v172
	v_lshlrev_b64 v[158:159], 6, v[172:173]
	v_ashrrev_i32_e32 v161, 31, v160
	v_lshl_add_u64 v[158:159], v[144:145], 0, v[158:159]
	v_lshlrev_b64 v[160:161], 6, v[160:161]
	v_lshl_add_u64 v[160:161], v[144:145], 0, v[160:161]
	global_load_dwordx4 v[182:185], v[158:159], off
	global_load_dwordx4 v[186:189], v[160:161], off
	v_or_b32_e32 v158, 32, v172
	v_ashrrev_i32_e32 v159, 31, v158
	v_lshlrev_b64 v[158:159], 6, v[158:159]
	v_lshl_add_u64 v[158:159], v[144:145], 0, v[158:159]
	global_load_dwordx4 v[190:193], v[158:159], off
	v_or_b32_e32 v158, 48, v172
	v_ashrrev_i32_e32 v159, 31, v158
	v_lshlrev_b64 v[158:159], 6, v[158:159]
	v_lshl_add_u64 v[158:159], v[144:145], 0, v[158:159]
	global_load_dwordx4 v[194:197], v[158:159], off
	v_add_u32_e32 v164, 0x80, v172
	v_ashrrev_i32_e32 v165, 31, v164
	v_lshlrev_b64 v[158:159], 6, v[164:165]
	v_add_u32_e32 v162, 0x90, v172
	v_lshl_add_u64 v[158:159], v[144:145], 0, v[158:159]
	v_ashrrev_i32_e32 v163, 31, v162
	global_load_dwordx4 v[198:201], v[158:159], off
	v_lshlrev_b64 v[158:159], 6, v[162:163]
	v_lshl_add_u64 v[158:159], v[144:145], 0, v[158:159]
	global_load_dwordx4 v[202:205], v[158:159], off
	v_and_b32_e32 v159, 64, v180
	v_xor_b32_e32 v158, 16, v180
	v_add_u32_e32 v159, 64, v159
	v_xor_b32_e32 v160, 32, v180
	v_cmp_lt_i32_e32 vcc, v158, v159
	v_mov_b64_e32 v[214:215], s[30:31]
	s_nop 0
	v_cndmask_b32_e32 v161, v180, v158, vcc
	v_cmp_lt_i32_e32 vcc, v160, v159
	v_add_u32_e32 v158, 0xb0, v172
	v_lshlrev_b32_e32 v163, 2, v161
	v_cndmask_b32_e32 v159, v180, v160, vcc
	v_add_u32_e32 v160, 0xa0, v172
	v_lshlrev_b32_e32 v165, 2, v159
	v_ashrrev_i32_e32 v161, 31, v160
	v_ashrrev_i32_e32 v159, 31, v158
	v_lshlrev_b64 v[170:171], 6, v[160:161]
	v_lshlrev_b64 v[206:207], 6, v[158:159]
	v_lshl_add_u64 v[170:171], v[144:145], 0, v[170:171]
	v_lshl_add_u64 v[210:211], v[144:145], 0, v[206:207]
	global_load_dwordx4 v[206:209], v[170:171], off
	s_nop 0
	global_load_dwordx4 v[210:213], v[210:211], off
	s_waitcnt vmcnt(0)
	v_mov_b32_e32 v170, v183
	v_mov_b32_e32 v171, v184
	v_mov_b32_e32 v183, v185
	v_pk_add_f32 v[170:171], v[170:171], v[182:183]
	v_mov_b32_e32 v182, v187
	v_mov_b32_e32 v183, v188
	v_mov_b32_e32 v187, v189
	v_mov_b32_e32 v184, v191
	v_mov_b32_e32 v185, v192
	v_mov_b32_e32 v191, v193
	v_pk_add_f32 v[182:183], v[182:183], v[186:187]
	v_mov_b32_e32 v188, v195
	v_mov_b32_e32 v189, v196
	v_mov_b32_e32 v195, v197
	v_mov_b32_e32 v187, v170
	v_pk_add_f32 v[184:185], v[184:185], v[190:191]
	v_pk_add_f32 v[188:189], v[188:189], v[194:195]
	v_mov_b32_e32 v186, v182
	v_mov_b32_e32 v170, v183
	v_mov_b32_e32 v182, v188
	v_mov_b32_e32 v183, v184
	v_mov_b32_e32 v184, v189
	v_pk_add_f32 v[170:171], v[186:187], v[170:171]
	v_pk_add_f32 v[182:183], v[182:183], v[184:185]
	ds_bpermute_b32 v185, v163, v171
	ds_bpermute_b32 v184, v163, v170
	ds_bpermute_b32 v187, v163, v183
	ds_bpermute_b32 v186, v163, v182
	v_mov_b32_e32 v188, v199
	v_mov_b32_e32 v189, v200
	s_waitcnt lgkmcnt(0)
	v_pk_add_f32 v[170:171], v[170:171], v[184:185]
	ds_bpermute_b32 v185, v165, v171
	ds_bpermute_b32 v184, v165, v170
	v_pk_add_f32 v[182:183], v[182:183], v[186:187]
	ds_bpermute_b32 v187, v165, v183
	ds_bpermute_b32 v186, v165, v182
	v_mov_b32_e32 v199, v201
	s_waitcnt lgkmcnt(2)
	v_pk_add_f32 v[170:171], v[170:171], v[184:185]
	v_mov_b32_e32 v190, v203
	v_pk_fma_f32 v[170:171], v[170:171], s[28:29], v[214:215] op_sel_hi:[1,0,0]
	v_mov_b32_e32 v191, v204
	v_mul_f32_e32 v159, 0x4b800000, v171
	v_mul_f32_e32 v161, 0x4b800000, v170
	v_cmp_gt_f32_e32 vcc, s59, v171
	v_cmp_gt_f32_e64 s[10:11], s59, v170
	v_mov_b32_e32 v203, v205
	v_pk_add_f32 v[188:189], v[188:189], v[198:199]
	v_cndmask_b32_e32 v159, v171, v159, vcc
	v_cndmask_b32_e64 v161, v170, v161, s[10:11]
	v_pk_add_f32 v[170:171], v[190:191], v[202:203]
	s_waitcnt lgkmcnt(0)
	v_pk_add_f32 v[182:183], v[182:183], v[186:187]
	v_mov_b32_e32 v186, v170
	v_mov_b32_e32 v187, v188
	v_mov_b32_e32 v188, v171
	v_pk_add_f32 v[170:171], v[186:187], v[188:189]
	v_rsq_f32_e32 v159, v159
	ds_bpermute_b32 v187, v163, v171
	ds_bpermute_b32 v186, v163, v170
	v_pk_fma_f32 v[182:183], v[182:183], s[28:29], v[214:215] op_sel_hi:[1,0,0]
	v_mul_f32_e32 v168, 0x45800000, v159
	v_mul_f32_e32 v166, 0x4b800000, v183
	v_cmp_gt_f32_e64 s[12:13], s59, v183
	v_cndmask_b32_e32 v184, v159, v168, vcc
	v_mul_f32_e32 v159, 0x4b800000, v182
	v_cmp_gt_f32_e32 vcc, s59, v182
	s_waitcnt lgkmcnt(0)
	v_pk_add_f32 v[170:171], v[170:171], v[186:187]
	v_cndmask_b32_e64 v166, v183, v166, s[12:13]
	v_cndmask_b32_e32 v159, v182, v159, vcc
	ds_bpermute_b32 v183, v165, v171
	ds_bpermute_b32 v182, v165, v170
	v_mov_b32_e32 v186, v211
	v_mov_b32_e32 v187, v212
	v_mov_b32_e32 v211, v213
	v_pk_add_f32 v[186:187], v[186:187], v[210:211]
	s_waitcnt lgkmcnt(0)
	v_pk_add_f32 v[170:171], v[170:171], v[182:183]
	v_mov_b32_e32 v182, v207
	v_mov_b32_e32 v183, v208
	v_mov_b32_e32 v207, v209
	v_pk_add_f32 v[182:183], v[182:183], v[206:207]
	v_mov_b32_e32 v188, v186
	v_mov_b32_e32 v189, v182
	v_mov_b32_e32 v182, v187
	v_pk_add_f32 v[182:183], v[188:189], v[182:183]
	ds_bpermute_b32 v187, v163, v183
	ds_bpermute_b32 v186, v163, v182
	v_rsq_f32_e32 v161, v161
	v_rsq_f32_e32 v166, v166
	v_pk_fma_f32 v[170:171], v[170:171], s[28:29], v[214:215] op_sel_hi:[1,0,0]
	v_rsq_f32_e32 v159, v159
	v_mul_f32_e32 v173, 0x45800000, v161
	s_waitcnt lgkmcnt(0)
; #define GAS __attribute__((address_space(1)))
; __device__ __forceinline__ float sigmoidf_fast(float z) { return fast_rcp(1.f + fast_exp2(-z * LOG2E)); }
; template <int NP>
; __device__ __forceinline__ void rows_rstd(const float* ssq, float invn, const Unit& u, int wr, int fr, int fq, float (&rs)[2][4]) {
;     ...
;       rs[ai][m] = rsqrtf(s * invn + RMS_EPS);
;     }
;   __device__ __forceinline__ void operator()(ACC_T, const Unit& u, int wr, int wc, int fr, int fq) const {
;     float rs[2][4]; rows_rstd<16>(ssq, 1.0f / DM, u, wr, fr, fq, rs);
; #pragma unroll
;     for (int ai = 0; ai < 2; ++ai)
; #pragma unroll
;       for (int m = 0; m < 4; ++m) {
;         const int row = erow(u, ai, wr, m, fr); const float r = rs[ai][m];
;         float v[8];
; #pragma unroll
;         for (int n = 0; n < 2; ++n)
; #pragma unroll
;           for (int j = 0; j < 4; ++j) {
;             const float g = acc[ai][0][m][n][j] * r, uu = acc[ai][1][m][n][j] * r;
;             v[4 * n + j] = g * sigmoidf_fast(g) * uu;
;           }
;         u32x4 w; w.x = pk_bf16(v[0], v[1]); w.y = pk_bf16(v[2], v[3]); w.z = pk_bf16(v[4], v[5]); w.w = pk_bf16(v[6], v[7]);
;         *(GAS u32x4*)(act + (size_t)row * DFF + 128 * u.pn + 32 * wc + 8 * fq) = w;
	v_pk_add_f32 v[182:183], v[182:183], v[186:187]
	v_cndmask_b32_e64 v178, v161, v173, s[10:11]
	v_mul_f32_e32 v161, 0x45800000, v166
	ds_bpermute_b32 v187, v165, v183
	ds_bpermute_b32 v186, v165, v182
	v_cndmask_b32_e64 v176, v166, v161, s[12:13]
	v_mul_f32_e32 v166, 0x4b800000, v171
	v_cmp_gt_f32_e64 s[10:11], s59, v171
	v_mul_f32_e32 v161, 0x45800000, v159
	s_waitcnt lgkmcnt(0)
	v_pk_add_f32 v[182:183], v[182:183], v[186:187]
	v_cndmask_b32_e64 v166, v171, v166, s[10:11]
	v_rsq_f32_e32 v166, v166
	v_mul_f32_e32 v163, 0x4b800000, v170
	v_cmp_gt_f32_e64 s[12:13], s59, v170
	v_pk_fma_f32 v[182:183], v[182:183], s[28:29], v[214:215] op_sel_hi:[1,0,0]
	v_cndmask_b32_e32 v174, v159, v161, vcc
	v_cndmask_b32_e64 v163, v170, v163, s[12:13]
	v_mul_f32_e32 v159, 0x45800000, v166
	v_mul_f32_e32 v161, 0x4b800000, v183
	v_cmp_gt_f32_e32 vcc, s59, v183
	v_rsq_f32_e32 v163, v163
	v_cndmask_b32_e64 v170, v166, v159, s[10:11]
	v_cndmask_b32_e32 v161, v183, v161, vcc
	v_mul_f32_e32 v165, 0x4b800000, v182
	v_cmp_gt_f32_e64 s[10:11], s59, v182
	v_rsq_f32_e32 v161, v161
	v_mul_f32_e32 v159, 0x45800000, v163
	v_cndmask_b32_e64 v165, v182, v165, s[10:11]
	v_rsq_f32_e32 v165, v165
	v_cndmask_b32_e64 v168, v163, v159, s[12:13]
	v_mul_f32_e32 v159, 0x45800000, v161
	v_cndmask_b32_e32 v166, v161, v159, vcc
	v_mul_f32_e32 v159, 0x45800000, v165
	v_cndmask_b32_e64 v186, v165, v159, s[10:11]
	v_lshlrev_b32_e32 v255, 2, v254
	v_add_u32_e32 v255, 0x20010, v255
	ds_write_b32 v255, v184
	ds_write_b32 v255, v178 offset:2048
	ds_write_b32 v255, v176 offset:4096
	ds_write_b32 v255, v174 offset:6144
	ds_write_b32 v255, v170 offset:8192
	ds_write_b32 v255, v168 offset:10240
	ds_write_b32 v255, v166 offset:12288
	ds_write_b32 v255, v186 offset:14336
	s_mov_b32 s100, s12
	s_branch .Lrsc_join_1
.Lrsc_hit_1:
	v_add_u32_e32 v172, s68, v167
	v_lshlrev_b32_e32 v255, 2, v254
	v_add_u32_e32 v255, 0x20010, v255
	ds_read_b32 v184, v255
	ds_read_b32 v178, v255 offset:2048
	ds_read_b32 v176, v255 offset:4096
	ds_read_b32 v174, v255 offset:6144
	ds_read_b32 v170, v255 offset:8192
	ds_read_b32 v168, v255 offset:10240
	ds_read_b32 v166, v255 offset:12288
	ds_read_b32 v186, v255 offset:14336
	v_add_u32_e32 v164, 0x80, v172
	v_add_u32_e32 v162, 0x90, v172
	v_add_u32_e32 v160, 0xa0, v172
	v_add_u32_e32 v158, 0xb0, v172
	s_waitcnt lgkmcnt(0)
.Lrsc_join_1:
	v_pk_mul_f32 v[182:183], v[124:125], v[184:185] op_sel_hi:[1,0]
	v_mul_f32_e32 v124, 0xbfb8aa3b, v182
	v_exp_f32_e32 v125, v124
	v_mov_b32_e32 v124, v186
	v_mul_f32_e32 v159, 0xbfb8aa3b, v183
	v_exp_f32_e32 v159, v159
	v_add_f32_e32 v125, 1.0, v125
	v_pk_mul_f32 v[126:127], v[126:127], v[184:185] op_sel_hi:[1,0]
	v_rcp_f32_e32 v186, v125
	v_add_f32_e32 v125, 1.0, v159
	v_mul_f32_e32 v159, 0xbfb8aa3b, v126
	v_exp_f32_e32 v159, v159
	v_mul_f32_e32 v161, 0xbfb8aa3b, v127
	v_exp_f32_e32 v161, v161
	v_rcp_f32_e32 v187, v125
	v_add_f32_e32 v125, 1.0, v159
	v_rcp_f32_e32 v188, v125
	v_add_f32_e32 v125, 1.0, v161
	v_rcp_f32_e32 v189, v125
	v_pk_mul_f32 v[116:117], v[116:117], v[184:185] op_sel_hi:[1,0]
	v_pk_mul_f32 v[122:123], v[122:123], v[184:185] op_sel_hi:[1,0]
	v_mul_f32_e32 v125, 0xbfb8aa3b, v116
	v_pk_mul_f32 v[126:127], v[126:127], v[188:189]
	v_exp_f32_e32 v125, v125
	v_pk_mul_f32 v[122:123], v[122:123], v[126:127]
	v_mul_f32_e32 v126, 0xbfb8aa3b, v117
	v_exp_f32_e32 v127, v126
	v_add_f32_e32 v125, 1.0, v125
	v_pk_mul_f32 v[118:119], v[118:119], v[184:185] op_sel_hi:[1,0]
	v_rcp_f32_e32 v126, v125
	v_add_f32_e32 v125, 1.0, v127
	v_mul_f32_e32 v127, 0xbfb8aa3b, v118
	v_exp_f32_e32 v159, v127
	v_mul_f32_e32 v127, 0xbfb8aa3b, v119
	v_exp_f32_e32 v161, v127
	v_pk_mul_f32 v[120:121], v[120:121], v[184:185] op_sel_hi:[1,0]
	v_pk_mul_f32 v[182:183], v[182:183], v[186:187]
	v_rcp_f32_e32 v127, v125
	v_add_f32_e32 v125, 1.0, v159
	v_pk_mul_f32 v[120:121], v[120:121], v[182:183]
	v_rcp_f32_e32 v182, v125
	v_add_f32_e32 v125, 1.0, v161
	v_rcp_f32_e32 v183, v125
	v_pk_mul_f32 v[112:113], v[112:113], v[184:185] op_sel_hi:[1,0]
	v_pk_mul_f32 v[116:117], v[116:117], v[126:127]
	v_pk_mul_f32 v[108:109], v[108:109], v[178:179] op_sel_hi:[1,0]
	v_pk_mul_f32 v[116:117], v[112:113], v[116:117]
	v_pk_mul_f32 v[112:113], v[114:115], v[184:185] op_sel_hi:[1,0]
	v_pk_mul_f32 v[114:115], v[118:119], v[182:183]
	v_pk_mul_f32 v[110:111], v[110:111], v[178:179] op_sel_hi:[1,0]
	v_pk_mul_f32 v[118:119], v[112:113], v[114:115]
	v_cvt_pk_bf16_f32 v114, v116, v117
	v_mad_i64_i32 v[116:117], s[10:11], v172, s60, v[130:131]
	s_lshl_b32 s10, s67, 7
	s_ashr_i32 s11, s10, 31
	s_lshl_b64 s[10:11], s[10:11], 1
	v_lshl_add_u64 v[116:117], v[116:117], 0, s[10:11]
	v_lshl_add_u64 v[116:117], v[116:117], 0, s[20:21]
	v_cvt_pk_bf16_f32 v112, v120, v121
	v_cvt_pk_bf16_f32 v113, v122, v123
	v_cvt_pk_bf16_f32 v115, v118, v119
	v_lshl_add_u64 v[116:117], v[116:117], 0, v[142:143]
	global_store_dwordx4 v[116:117], v[112:115], off
	v_pk_mul_f32 v[104:105], v[104:105], v[178:179] op_sel_hi:[1,0]
	v_pk_mul_f32 v[100:101], v[100:101], v[178:179] op_sel_hi:[1,0]
	v_mul_f32_e32 v112, 0xbfb8aa3b, v108
	v_mul_f32_e32 v113, 0xbfb8aa3b, v109
	v_exp_f32_e32 v112, v112
	v_exp_f32_e32 v113, v113
	v_mul_f32_e32 v114, 0xbfb8aa3b, v110
	v_mul_f32_e32 v115, 0xbfb8aa3b, v111
	v_exp_f32_e32 v114, v114
	v_exp_f32_e32 v115, v115
	v_add_f32_e32 v112, 1.0, v112
	v_add_f32_e32 v113, 1.0, v113
	v_rcp_f32_e32 v112, v112
	v_rcp_f32_e32 v113, v113
	v_add_f32_e32 v114, 1.0, v114
	v_add_f32_e32 v115, 1.0, v115
	v_rcp_f32_e32 v114, v114
	v_rcp_f32_e32 v115, v115
	v_pk_mul_f32 v[108:109], v[108:109], v[112:113]
	v_pk_mul_f32 v[106:107], v[106:107], v[178:179] op_sel_hi:[1,0]
	v_pk_mul_f32 v[104:105], v[104:105], v[108:109]
; #define GAS __attribute__((address_space(1)))
; __device__ __forceinline__ float sigmoidf_fast(float z) { return fast_rcp(1.f + fast_exp2(-z * LOG2E)); }
; #define ROW_FENCE() asm volatile("" ::: "memory")
;   __device__ __forceinline__ void operator()(ACC_T, const Unit& u, int wr, int wc, int fr, int fq) const {
;     ...
;     for (int ai = 0; ai < 2; ++ai)
; #pragma unroll
;       for (int m = 0; m < 4; ++m) {
;         const int row = erow(u, ai, wr, m, fr); const float r = rs[ai][m];
;         float v[8];
; #pragma unroll
;         for (int n = 0; n < 2; ++n)
; #pragma unroll
;           for (int j = 0; j < 4; ++j) {
;             const float g = acc[ai][0][m][n][j] * r, uu = acc[ai][1][m][n][j] * r;
;             v[4 * n + j] = g * sigmoidf_fast(g) * uu;
;           }
;         u32x4 w; w.x = pk_bf16(v[0], v[1]); w.y = pk_bf16(v[2], v[3]); w.z = pk_bf16(v[4], v[5]); w.w = pk_bf16(v[6], v[7]);
;         *(GAS u32x4*)(act + (size_t)row * DFF + 128 * u.pn + 32 * wc + 8 * fq) = w;
;         ROW_FENCE();
	v_pk_mul_f32 v[108:109], v[110:111], v[114:115]
	v_mul_f32_e32 v110, 0xbfb8aa3b, v100
	v_exp_f32_e32 v110, v110
	v_pk_mul_f32 v[106:107], v[106:107], v[108:109]
	v_mul_f32_e32 v108, 0xbfb8aa3b, v101
	v_pk_mul_f32 v[102:103], v[102:103], v[178:179] op_sel_hi:[1,0]
	v_exp_f32_e32 v109, v108
	v_add_f32_e32 v108, 1.0, v110
	v_mul_f32_e32 v110, 0xbfb8aa3b, v102
	v_mul_f32_e32 v111, 0xbfb8aa3b, v103
	v_exp_f32_e32 v110, v110
	v_exp_f32_e32 v111, v111
	v_add_f32_e32 v109, 1.0, v109
	v_rcp_f32_e32 v108, v108
	v_rcp_f32_e32 v109, v109
	v_add_f32_e32 v110, 1.0, v110
	v_add_f32_e32 v111, 1.0, v111
	v_rcp_f32_e32 v110, v110
	v_rcp_f32_e32 v111, v111
	v_pk_mul_f32 v[96:97], v[96:97], v[178:179] op_sel_hi:[1,0]
	v_pk_mul_f32 v[100:101], v[100:101], v[108:109]
	v_add_u32_e32 v108, s68, v181
	v_pk_mul_f32 v[100:101], v[96:97], v[100:101]
	v_pk_mul_f32 v[96:97], v[98:99], v[178:179] op_sel_hi:[1,0]
	v_pk_mul_f32 v[98:99], v[102:103], v[110:111]
	v_pk_mul_f32 v[92:93], v[92:93], v[176:177] op_sel_hi:[1,0]
	v_pk_mul_f32 v[102:103], v[96:97], v[98:99]
	v_cvt_pk_bf16_f32 v98, v100, v101
	v_mad_i64_i32 v[100:101], s[12:13], v108, s60, v[130:131]
	v_lshl_add_u64 v[100:101], v[100:101], 0, s[10:11]
	v_lshl_add_u64 v[100:101], v[100:101], 0, s[20:21]
	v_cvt_pk_bf16_f32 v96, v104, v105
	v_cvt_pk_bf16_f32 v97, v106, v107
	v_cvt_pk_bf16_f32 v99, v102, v103
	v_lshl_add_u64 v[100:101], v[100:101], 0, v[142:143]
	global_store_dwordx4 v[100:101], v[96:99], off
	v_pk_mul_f32 v[94:95], v[94:95], v[176:177] op_sel_hi:[1,0]
	v_pk_mul_f32 v[88:89], v[88:89], v[176:177] op_sel_hi:[1,0]
	v_mul_f32_e32 v96, 0xbfb8aa3b, v92
	v_mul_f32_e32 v97, 0xbfb8aa3b, v93
	v_exp_f32_e32 v96, v96
	v_exp_f32_e32 v97, v97
	v_mul_f32_e32 v98, 0xbfb8aa3b, v94
	v_mul_f32_e32 v99, 0xbfb8aa3b, v95
	v_exp_f32_e32 v98, v98
	v_exp_f32_e32 v99, v99
	v_add_f32_e32 v96, 1.0, v96
	v_add_f32_e32 v97, 1.0, v97
	v_rcp_f32_e32 v96, v96
	v_rcp_f32_e32 v97, v97
	v_add_f32_e32 v98, 1.0, v98
	v_add_f32_e32 v99, 1.0, v99
	v_rcp_f32_e32 v98, v98
	v_rcp_f32_e32 v99, v99
	v_pk_mul_f32 v[92:93], v[92:93], v[96:97]
	v_pk_mul_f32 v[84:85], v[84:85], v[176:177] op_sel_hi:[1,0]
	v_pk_mul_f32 v[88:89], v[88:89], v[92:93]
	v_pk_mul_f32 v[92:93], v[94:95], v[98:99]
	v_mul_f32_e32 v94, 0xbfb8aa3b, v84
	v_exp_f32_e32 v94, v94
	v_pk_mul_f32 v[90:91], v[90:91], v[176:177] op_sel_hi:[1,0]
	v_pk_mul_f32 v[86:87], v[86:87], v[176:177] op_sel_hi:[1,0]
	v_pk_mul_f32 v[90:91], v[90:91], v[92:93]
	v_mul_f32_e32 v92, 0xbfb8aa3b, v85
	v_exp_f32_e32 v93, v92
	v_add_f32_e32 v92, 1.0, v94
	v_mul_f32_e32 v94, 0xbfb8aa3b, v86
	v_mul_f32_e32 v95, 0xbfb8aa3b, v87
	v_exp_f32_e32 v94, v94
	v_exp_f32_e32 v95, v95
	v_add_f32_e32 v93, 1.0, v93
	v_rcp_f32_e32 v92, v92
	v_rcp_f32_e32 v93, v93
	v_add_f32_e32 v94, 1.0, v94
	v_add_f32_e32 v95, 1.0, v95
	v_rcp_f32_e32 v94, v94
	v_rcp_f32_e32 v95, v95
	v_pk_mul_f32 v[80:81], v[80:81], v[176:177] op_sel_hi:[1,0]
	v_pk_mul_f32 v[84:85], v[84:85], v[92:93]
	v_add_u32_e32 v92, s68, v175
	v_pk_mul_f32 v[84:85], v[80:81], v[84:85]
	v_pk_mul_f32 v[80:81], v[82:83], v[176:177] op_sel_hi:[1,0]
	v_pk_mul_f32 v[82:83], v[86:87], v[94:95]
	v_pk_mul_f32 v[76:77], v[76:77], v[174:175] op_sel_hi:[1,0]
	v_pk_mul_f32 v[86:87], v[80:81], v[82:83]
	v_cvt_pk_bf16_f32 v82, v84, v85
	v_mad_i64_i32 v[84:85], s[12:13], v92, s60, v[130:131]
	v_lshl_add_u64 v[84:85], v[84:85], 0, s[10:11]
	v_lshl_add_u64 v[84:85], v[84:85], 0, s[20:21]
	v_cvt_pk_bf16_f32 v80, v88, v89
	v_cvt_pk_bf16_f32 v81, v90, v91
	v_cvt_pk_bf16_f32 v83, v86, v87
	v_lshl_add_u64 v[84:85], v[84:85], 0, v[142:143]
	global_store_dwordx4 v[84:85], v[80:83], off
	v_pk_mul_f32 v[78:79], v[78:79], v[174:175] op_sel_hi:[1,0]
	v_pk_mul_f32 v[72:73], v[72:73], v[174:175] op_sel_hi:[1,0]
	v_mul_f32_e32 v80, 0xbfb8aa3b, v76
	v_mul_f32_e32 v81, 0xbfb8aa3b, v77
	v_exp_f32_e32 v80, v80
	v_exp_f32_e32 v81, v81
	v_mul_f32_e32 v82, 0xbfb8aa3b, v78
	v_mul_f32_e32 v83, 0xbfb8aa3b, v79
	v_exp_f32_e32 v82, v82
	v_exp_f32_e32 v83, v83
	v_add_f32_e32 v80, 1.0, v80
	v_add_f32_e32 v81, 1.0, v81
	v_rcp_f32_e32 v80, v80
	v_rcp_f32_e32 v81, v81
	v_add_f32_e32 v82, 1.0, v82
	v_add_f32_e32 v83, 1.0, v83
	v_rcp_f32_e32 v82, v82
	v_rcp_f32_e32 v83, v83
	v_pk_mul_f32 v[76:77], v[76:77], v[80:81]
	v_pk_mul_f32 v[68:69], v[68:69], v[174:175] op_sel_hi:[1,0]
	v_pk_mul_f32 v[72:73], v[72:73], v[76:77]
	v_pk_mul_f32 v[76:77], v[78:79], v[82:83]
	v_mul_f32_e32 v78, 0xbfb8aa3b, v68
	v_exp_f32_e32 v78, v78
	v_pk_mul_f32 v[74:75], v[74:75], v[174:175] op_sel_hi:[1,0]
	v_pk_mul_f32 v[70:71], v[70:71], v[174:175] op_sel_hi:[1,0]
	v_pk_mul_f32 v[74:75], v[74:75], v[76:77]
	v_mul_f32_e32 v76, 0xbfb8aa3b, v69
	v_exp_f32_e32 v77, v76
	v_add_f32_e32 v76, 1.0, v78
	v_mul_f32_e32 v78, 0xbfb8aa3b, v70
	v_mul_f32_e32 v79, 0xbfb8aa3b, v71
	v_exp_f32_e32 v78, v78
	v_exp_f32_e32 v79, v79
	v_add_f32_e32 v77, 1.0, v77
	v_rcp_f32_e32 v76, v76
	v_rcp_f32_e32 v77, v77
	v_add_f32_e32 v78, 1.0, v78
	v_add_f32_e32 v79, 1.0, v79
	v_rcp_f32_e32 v78, v78
	v_rcp_f32_e32 v79, v79
	v_pk_mul_f32 v[64:65], v[64:65], v[174:175] op_sel_hi:[1,0]
	v_pk_mul_f32 v[68:69], v[68:69], v[76:77]
	v_add_u32_e32 v76, s68, v177
	v_pk_mul_f32 v[68:69], v[64:65], v[68:69]
	v_pk_mul_f32 v[64:65], v[66:67], v[174:175] op_sel_hi:[1,0]
	v_pk_mul_f32 v[66:67], v[70:71], v[78:79]
	v_pk_mul_f32 v[60:61], v[60:61], v[170:171] op_sel_hi:[1,0]
	v_pk_mul_f32 v[70:71], v[64:65], v[66:67]
	v_cvt_pk_bf16_f32 v66, v68, v69
	v_mad_i64_i32 v[68:69], s[12:13], v76, s60, v[130:131]
	v_lshl_add_u64 v[68:69], v[68:69], 0, s[10:11]
	v_lshl_add_u64 v[68:69], v[68:69], 0, s[20:21]
	v_cvt_pk_bf16_f32 v64, v72, v73
	v_cvt_pk_bf16_f32 v65, v74, v75
	v_cvt_pk_bf16_f32 v67, v70, v71
; #define GAS __attribute__((address_space(1)))
; __device__ __forceinline__ float sigmoidf_fast(float z) { return fast_rcp(1.f + fast_exp2(-z * LOG2E)); }
; #define ROW_FENCE() asm volatile("" ::: "memory")
;   __device__ __forceinline__ void operator()(ACC_T, const Unit& u, int wr, int wc, int fr, int fq) const {
;     ...
;     for (int ai = 0; ai < 2; ++ai)
; #pragma unroll
;       for (int m = 0; m < 4; ++m) {
;         const int row = erow(u, ai, wr, m, fr); const float r = rs[ai][m];
;         float v[8];
; #pragma unroll
;         for (int n = 0; n < 2; ++n)
; #pragma unroll
;           for (int j = 0; j < 4; ++j) {
;             const float g = acc[ai][0][m][n][j] * r, uu = acc[ai][1][m][n][j] * r;
;             v[4 * n + j] = g * sigmoidf_fast(g) * uu;
;           }
;         u32x4 w; w.x = pk_bf16(v[0], v[1]); w.y = pk_bf16(v[2], v[3]); w.z = pk_bf16(v[4], v[5]); w.w = pk_bf16(v[6], v[7]);
;         *(GAS u32x4*)(act + (size_t)row * DFF + 128 * u.pn + 32 * wc + 8 * fq) = w;
;         ROW_FENCE();
	v_lshl_add_u64 v[68:69], v[68:69], 0, v[142:143]
	global_store_dwordx4 v[68:69], v[64:67], off
	v_pk_mul_f32 v[62:63], v[62:63], v[170:171] op_sel_hi:[1,0]
	v_pk_mul_f32 v[56:57], v[56:57], v[170:171] op_sel_hi:[1,0]
	v_mul_f32_e32 v64, 0xbfb8aa3b, v60
	v_mul_f32_e32 v65, 0xbfb8aa3b, v61
	v_exp_f32_e32 v64, v64
	v_exp_f32_e32 v65, v65
	v_mul_f32_e32 v66, 0xbfb8aa3b, v62
	v_mul_f32_e32 v67, 0xbfb8aa3b, v63
	v_exp_f32_e32 v66, v66
	v_exp_f32_e32 v67, v67
	v_add_f32_e32 v64, 1.0, v64
	v_add_f32_e32 v65, 1.0, v65
	v_rcp_f32_e32 v64, v64
	v_rcp_f32_e32 v65, v65
	v_add_f32_e32 v66, 1.0, v66
	v_add_f32_e32 v67, 1.0, v67
	v_rcp_f32_e32 v66, v66
	v_rcp_f32_e32 v67, v67
	v_pk_mul_f32 v[60:61], v[60:61], v[64:65]
	v_pk_mul_f32 v[52:53], v[52:53], v[170:171] op_sel_hi:[1,0]
	v_pk_mul_f32 v[56:57], v[56:57], v[60:61]
	v_pk_mul_f32 v[60:61], v[62:63], v[66:67]
	v_mul_f32_e32 v62, 0xbfb8aa3b, v52
	v_exp_f32_e32 v62, v62
	v_pk_mul_f32 v[58:59], v[58:59], v[170:171] op_sel_hi:[1,0]
	v_pk_mul_f32 v[54:55], v[54:55], v[170:171] op_sel_hi:[1,0]
	v_pk_mul_f32 v[58:59], v[58:59], v[60:61]
	v_mul_f32_e32 v60, 0xbfb8aa3b, v53
	v_exp_f32_e32 v61, v60
	v_add_f32_e32 v60, 1.0, v62
	v_mul_f32_e32 v62, 0xbfb8aa3b, v54
	v_mul_f32_e32 v63, 0xbfb8aa3b, v55
	v_exp_f32_e32 v62, v62
	v_exp_f32_e32 v63, v63
	v_add_f32_e32 v61, 1.0, v61
	v_rcp_f32_e32 v60, v60
	v_rcp_f32_e32 v61, v61
	v_add_f32_e32 v62, 1.0, v62
	v_add_f32_e32 v63, 1.0, v63
	v_rcp_f32_e32 v62, v62
	v_rcp_f32_e32 v63, v63
	v_pk_mul_f32 v[48:49], v[48:49], v[170:171] op_sel_hi:[1,0]
	v_pk_mul_f32 v[52:53], v[52:53], v[60:61]
	v_pk_mul_f32 v[44:45], v[44:45], v[168:169] op_sel_hi:[1,0]
	v_pk_mul_f32 v[52:53], v[48:49], v[52:53]
	v_pk_mul_f32 v[48:49], v[50:51], v[170:171] op_sel_hi:[1,0]
	v_pk_mul_f32 v[50:51], v[54:55], v[62:63]
	v_pk_mul_f32 v[46:47], v[46:47], v[168:169] op_sel_hi:[1,0]
	v_pk_mul_f32 v[54:55], v[48:49], v[50:51]
	v_cvt_pk_bf16_f32 v50, v52, v53
	v_mad_i64_i32 v[52:53], s[12:13], v164, s60, v[130:131]
	v_lshl_add_u64 v[52:53], v[52:53], 0, s[10:11]
	v_lshl_add_u64 v[52:53], v[52:53], 0, s[20:21]
	v_cvt_pk_bf16_f32 v48, v56, v57
	v_cvt_pk_bf16_f32 v49, v58, v59
	v_cvt_pk_bf16_f32 v51, v54, v55
	v_lshl_add_u64 v[52:53], v[52:53], 0, v[142:143]
	global_store_dwordx4 v[52:53], v[48:51], off
	v_pk_mul_f32 v[40:41], v[40:41], v[168:169] op_sel_hi:[1,0]
	v_pk_mul_f32 v[36:37], v[36:37], v[168:169] op_sel_hi:[1,0]
	v_mul_f32_e32 v48, 0xbfb8aa3b, v44
	v_mul_f32_e32 v49, 0xbfb8aa3b, v45
	v_exp_f32_e32 v48, v48
	v_exp_f32_e32 v49, v49
	v_mul_f32_e32 v50, 0xbfb8aa3b, v46
	v_mul_f32_e32 v51, 0xbfb8aa3b, v47
	v_exp_f32_e32 v50, v50
	v_exp_f32_e32 v51, v51
	v_add_f32_e32 v48, 1.0, v48
	v_add_f32_e32 v49, 1.0, v49
	v_rcp_f32_e32 v48, v48
	v_rcp_f32_e32 v49, v49
	v_add_f32_e32 v50, 1.0, v50
	v_add_f32_e32 v51, 1.0, v51
	v_rcp_f32_e32 v50, v50
	v_rcp_f32_e32 v51, v51
	v_pk_mul_f32 v[44:45], v[44:45], v[48:49]
	v_pk_mul_f32 v[42:43], v[42:43], v[168:169] op_sel_hi:[1,0]
	v_pk_mul_f32 v[40:41], v[40:41], v[44:45]
	v_pk_mul_f32 v[44:45], v[46:47], v[50:51]
	v_mul_f32_e32 v46, 0xbfb8aa3b, v36
	v_exp_f32_e32 v46, v46
	v_pk_mul_f32 v[42:43], v[42:43], v[44:45]
	v_mul_f32_e32 v44, 0xbfb8aa3b, v37
	v_pk_mul_f32 v[38:39], v[38:39], v[168:169] op_sel_hi:[1,0]
	v_exp_f32_e32 v45, v44
	v_add_f32_e32 v44, 1.0, v46
	v_mul_f32_e32 v46, 0xbfb8aa3b, v38
	v_mul_f32_e32 v47, 0xbfb8aa3b, v39
	v_exp_f32_e32 v46, v46
	v_exp_f32_e32 v47, v47
	v_add_f32_e32 v45, 1.0, v45
	v_rcp_f32_e32 v44, v44
	v_rcp_f32_e32 v45, v45
	v_add_f32_e32 v46, 1.0, v46
	v_add_f32_e32 v47, 1.0, v47
	v_rcp_f32_e32 v46, v46
	v_rcp_f32_e32 v47, v47
	v_pk_mul_f32 v[32:33], v[32:33], v[168:169] op_sel_hi:[1,0]
	v_pk_mul_f32 v[36:37], v[36:37], v[44:45]
	v_pk_mul_f32 v[28:29], v[28:29], v[166:167] op_sel_hi:[1,0]
	v_pk_mul_f32 v[36:37], v[32:33], v[36:37]
	v_pk_mul_f32 v[32:33], v[34:35], v[168:169] op_sel_hi:[1,0]
	v_pk_mul_f32 v[34:35], v[38:39], v[46:47]
	v_pk_mul_f32 v[30:31], v[30:31], v[166:167] op_sel_hi:[1,0]
	v_pk_mul_f32 v[38:39], v[32:33], v[34:35]
	v_cvt_pk_bf16_f32 v34, v36, v37
	v_mad_i64_i32 v[36:37], s[12:13], v162, s60, v[130:131]
	v_lshl_add_u64 v[36:37], v[36:37], 0, s[10:11]
	v_lshl_add_u64 v[36:37], v[36:37], 0, s[20:21]
	v_cvt_pk_bf16_f32 v32, v40, v41
	v_cvt_pk_bf16_f32 v33, v42, v43
	v_cvt_pk_bf16_f32 v35, v38, v39
; #define PG8_BAR __builtin_amdgcn_s_barrier()
; #define GAS __attribute__((address_space(1)))
; __device__ __forceinline__ float sigmoidf_fast(float z) { return fast_rcp(1.f + fast_exp2(-z * LOG2E)); }
; #define ROW_FENCE() asm volatile("" ::: "memory")
; template <class Epi, class Sched, bool ALIGN_EPI = false, bool SP2 = false>
; __device__ __forceinline__ void gemm_phase(PG8_LAS unsigned char* lds, const Gemm g, const Sched& S, const Epi& E) {
;     ...
;         if constexpr (!Epi::AFTER_DRAIN) { E(acc, cur, wr, wc, fr, fq); S.done(cur); }
;         if (!has_next) break;
; #pragma unroll
;         for (int a = 0; a < 2; ++a)
; #pragma unroll
;             for (int b = 0; b < 2; ++b)
; #pragma unroll
;                 for (int m = 0; m < 4; ++m)
; #pragma unroll
;                     for (int n = 0; n < 2; ++n) acc[a][b][m][n] = (f32x4){0.f, 0.f, 0.f, 0.f};
;         cur = nxt; cA = nA; cB = nB; ++ui;
;         if constexpr (ALIGN_EPI) { if (wr == 1) PG8_BAR; }
;   __device__ __forceinline__ void operator()(ACC_T, const Unit& u, int wr, int wc, int fr, int fq) const {
;     ...
;     for (int ai = 0; ai < 2; ++ai)
; #pragma unroll
;       for (int m = 0; m < 4; ++m) {
;         const int row = erow(u, ai, wr, m, fr); const float r = rs[ai][m];
;         float v[8];
; #pragma unroll
;         for (int n = 0; n < 2; ++n)
; #pragma unroll
;           for (int j = 0; j < 4; ++j) {
;             const float g = acc[ai][0][m][n][j] * r, uu = acc[ai][1][m][n][j] * r;
;             v[4 * n + j] = g * sigmoidf_fast(g) * uu;
;           }
;         u32x4 w; w.x = pk_bf16(v[0], v[1]); w.y = pk_bf16(v[2], v[3]); w.z = pk_bf16(v[4], v[5]); w.w = pk_bf16(v[6], v[7]);
;         *(GAS u32x4*)(act + (size_t)row * DFF + 128 * u.pn + 32 * wc + 8 * fq) = w;
;         ROW_FENCE();
	v_lshl_add_u64 v[36:37], v[36:37], 0, v[142:143]
	global_store_dwordx4 v[36:37], v[32:35], off
	v_pk_mul_f32 v[24:25], v[24:25], v[166:167] op_sel_hi:[1,0]
	v_pk_mul_f32 v[20:21], v[20:21], v[166:167] op_sel_hi:[1,0]
	v_mul_f32_e32 v32, 0xbfb8aa3b, v28
	v_mul_f32_e32 v33, 0xbfb8aa3b, v29
	v_exp_f32_e32 v32, v32
	v_exp_f32_e32 v33, v33
	v_mul_f32_e32 v34, 0xbfb8aa3b, v30
	v_mul_f32_e32 v35, 0xbfb8aa3b, v31
	v_exp_f32_e32 v34, v34
	v_exp_f32_e32 v35, v35
	v_add_f32_e32 v32, 1.0, v32
	v_add_f32_e32 v33, 1.0, v33
	v_rcp_f32_e32 v32, v32
	v_rcp_f32_e32 v33, v33
	v_add_f32_e32 v34, 1.0, v34
	v_add_f32_e32 v35, 1.0, v35
	v_rcp_f32_e32 v34, v34
	v_rcp_f32_e32 v35, v35
	v_pk_mul_f32 v[28:29], v[28:29], v[32:33]
	v_pk_mul_f32 v[26:27], v[26:27], v[166:167] op_sel_hi:[1,0]
	v_pk_mul_f32 v[24:25], v[24:25], v[28:29]
	v_pk_mul_f32 v[28:29], v[30:31], v[34:35]
	v_mul_f32_e32 v30, 0xbfb8aa3b, v20
	v_exp_f32_e32 v30, v30
	v_pk_mul_f32 v[26:27], v[26:27], v[28:29]
	v_mul_f32_e32 v28, 0xbfb8aa3b, v21
	v_pk_mul_f32 v[22:23], v[22:23], v[166:167] op_sel_hi:[1,0]
	v_exp_f32_e32 v29, v28
	v_add_f32_e32 v28, 1.0, v30
	v_mul_f32_e32 v30, 0xbfb8aa3b, v22
	v_mul_f32_e32 v31, 0xbfb8aa3b, v23
	v_exp_f32_e32 v30, v30
	v_exp_f32_e32 v31, v31
	v_add_f32_e32 v29, 1.0, v29
	v_rcp_f32_e32 v28, v28
	v_rcp_f32_e32 v29, v29
	v_add_f32_e32 v30, 1.0, v30
	v_add_f32_e32 v31, 1.0, v31
	v_rcp_f32_e32 v30, v30
	v_rcp_f32_e32 v31, v31
	v_pk_mul_f32 v[16:17], v[16:17], v[166:167] op_sel_hi:[1,0]
	v_pk_mul_f32 v[20:21], v[20:21], v[28:29]
	v_pk_mul_f32 v[12:13], v[12:13], v[124:125] op_sel_hi:[1,0]
	v_pk_mul_f32 v[20:21], v[16:17], v[20:21]
	v_pk_mul_f32 v[16:17], v[18:19], v[166:167] op_sel_hi:[1,0]
	v_pk_mul_f32 v[18:19], v[22:23], v[30:31]
	v_pk_mul_f32 v[14:15], v[14:15], v[124:125] op_sel_hi:[1,0]
	v_pk_mul_f32 v[22:23], v[16:17], v[18:19]
	v_cvt_pk_bf16_f32 v18, v20, v21
	v_mad_i64_i32 v[20:21], s[12:13], v160, s60, v[130:131]
	v_lshl_add_u64 v[20:21], v[20:21], 0, s[10:11]
	v_lshl_add_u64 v[20:21], v[20:21], 0, s[20:21]
	v_cvt_pk_bf16_f32 v16, v24, v25
	v_cvt_pk_bf16_f32 v17, v26, v27
	v_cvt_pk_bf16_f32 v19, v22, v23
	v_lshl_add_u64 v[20:21], v[20:21], 0, v[142:143]
	global_store_dwordx4 v[20:21], v[16:19], off
	v_pk_mul_f32 v[8:9], v[8:9], v[124:125] op_sel_hi:[1,0]
	v_pk_mul_f32 v[4:5], v[4:5], v[124:125] op_sel_hi:[1,0]
	v_mul_f32_e32 v16, 0xbfb8aa3b, v12
	v_mul_f32_e32 v17, 0xbfb8aa3b, v13
	v_exp_f32_e32 v16, v16
	v_exp_f32_e32 v17, v17
	v_mul_f32_e32 v18, 0xbfb8aa3b, v14
	v_mul_f32_e32 v19, 0xbfb8aa3b, v15
	v_exp_f32_e32 v18, v18
	v_exp_f32_e32 v19, v19
	v_add_f32_e32 v16, 1.0, v16
	v_add_f32_e32 v17, 1.0, v17
	v_rcp_f32_e32 v16, v16
	v_rcp_f32_e32 v17, v17
	v_add_f32_e32 v18, 1.0, v18
	v_add_f32_e32 v19, 1.0, v19
	v_rcp_f32_e32 v18, v18
	v_rcp_f32_e32 v19, v19
	v_pk_mul_f32 v[12:13], v[12:13], v[16:17]
	v_pk_mul_f32 v[10:11], v[10:11], v[124:125] op_sel_hi:[1,0]
	v_pk_mul_f32 v[8:9], v[8:9], v[12:13]
	v_pk_mul_f32 v[12:13], v[14:15], v[18:19]
	v_mul_f32_e32 v14, 0xbfb8aa3b, v4
	v_exp_f32_e32 v14, v14
	v_pk_mul_f32 v[10:11], v[10:11], v[12:13]
	v_mul_f32_e32 v12, 0xbfb8aa3b, v5
	v_pk_mul_f32 v[6:7], v[6:7], v[124:125] op_sel_hi:[1,0]
	v_exp_f32_e32 v13, v12
	v_add_f32_e32 v12, 1.0, v14
	v_mul_f32_e32 v14, 0xbfb8aa3b, v6
	v_mul_f32_e32 v15, 0xbfb8aa3b, v7
	v_exp_f32_e32 v14, v14
	v_exp_f32_e32 v15, v15
	v_add_f32_e32 v13, 1.0, v13
	v_rcp_f32_e32 v12, v12
	v_rcp_f32_e32 v13, v13
	v_add_f32_e32 v14, 1.0, v14
	v_add_f32_e32 v15, 1.0, v15
	v_rcp_f32_e32 v14, v14
	v_rcp_f32_e32 v15, v15
	v_pk_mul_f32 v[0:1], v[0:1], v[124:125] op_sel_hi:[1,0]
	v_pk_mul_f32 v[4:5], v[4:5], v[12:13]
	s_and_b64 vcc, exec, s[8:9]
	v_pk_mul_f32 v[4:5], v[0:1], v[4:5]
	v_pk_mul_f32 v[0:1], v[2:3], v[124:125] op_sel_hi:[1,0]
	v_pk_mul_f32 v[2:3], v[6:7], v[14:15]
	s_mov_b64 s[8:9], -1
	v_pk_mul_f32 v[6:7], v[0:1], v[2:3]
	v_cvt_pk_bf16_f32 v2, v4, v5
	v_mad_i64_i32 v[4:5], s[12:13], v158, s60, v[130:131]
	v_lshl_add_u64 v[4:5], v[4:5], 0, s[10:11]
	v_lshl_add_u64 v[4:5], v[4:5], 0, s[20:21]
	v_cvt_pk_bf16_f32 v0, v8, v9
	v_cvt_pk_bf16_f32 v1, v10, v11
	v_cvt_pk_bf16_f32 v3, v6, v7
	v_lshl_add_u64 v[4:5], v[4:5], 0, v[142:143]
	global_store_dwordx4 v[4:5], v[0:3], off
	s_cbranch_vccnz .LBB0_1012
	s_andn2_b64 vcc, exec, s[18:19]
	s_cbranch_vccnz .LBB0_1011
	s_barrier
	s_branch .LBB0_1011

; __device__ __forceinline__ int tid_fresh() { int t = threadIdx.x; asm volatile("" : "+v"(t)); return t; }
; #define PG8_STAGE(bufoff, gbase, voff) do { _Pragma("unroll") for (int _i = 0; _i < 2; ++_i) \
;         __builtin_amdgcn_global_load_lds((const unsigned*)((const char*)(gbase) + (voff)[_i]), (PG8_LAS unsigned*)(lds + (bufoff) + ldsw + _i * 8192), 16, 0, 0); } while (0)
; #define PG8_BAR __builtin_amdgcn_s_barrier()
; template <class Epi, class Sched, bool ALIGN_EPI = false, bool SP2 = false>
; __device__ __forceinline__ void gemm_phase(PG8_LAS unsigned char* lds, const Gemm g, const Sched& S, const Epi& E) {
;     const int tid = tid_fresh(), wid = __builtin_amdgcn_readfirstlane(tid >> 6), lane = tid & 63, wr = wid >> 2, wc = wid & 3, fr = lane & 15, fq = lane >> 4;
;     const int K = g.K, nt = K / BK;
;     unsigned voffA[2], voffB[2];
; #pragma unroll
;     for (int i = 0; i < 2; ++i) { int R, C; stage_rc(tid * 16 + i * 8192, R, C); const int Rb = Epi::PERM ? ((R & ~31) + perm32(R & 31)) : R;
;         voffA[i] = (unsigned)(R * K + C) * 2u; voffB[i] = (unsigned)(Rb * K + C) * 2u; }
;     const size_t kstep = (size_t)(BK * 2);
;     const size_t hstep = (size_t)HALF * K * 2;
;     const size_t tstep = 2 * hstep;
;     const unsigned ldsw = (unsigned)wid * 1024u;
;     const int aoff = lds_byte(wr * 64 + fr, fq * 8), boff = lds_byte(wc * 32 + fr, fq * 8);
;     ...
;     Unit cur, nxt; int ui = 0;
;     if (!S.next(0, cur)) return;
;     f32x4 acc[2][2][4][2];
; #pragma unroll
;     for (int a = 0; a < 2; ++a)
; #pragma unroll
;         for (int b = 0; b < 2; ++b)
; #pragma unroll
;             for (int m = 0; m < 4; ++m)
; #pragma unroll
;                 for (int n = 0; n < 2; ++n) acc[a][b][m][n] = (f32x4){0.f, 0.f, 0.f, 0.f};
;     bf16x8 At[4][2], B0[2][2], B1[2][2];
;     const char* cA = (const char*)g.A + (size_t)cur.pm * tstep; const char* cB = (const char*)g.Bt + (size_t)cur.pn * tstep;
;     S.a_ready(cur);
;     if constexpr (SP2) {
;         PG8_STAGE(PG8_SB(0, 0), cB, voffB); PG8_STAGE(PG8_SB(0, 1), cB + hstep, voffB); PG8_STAGE(PG8_SA(0, 0), cA, voffA); PG8_STAGE(PG8_SA(0, 1), cA + hstep, voffA);
;         if (wr == 1) PG8_BAR;
.LBB0_1259:
	s_or_b64 exec, exec, s[46:47]
	s_mov_b64 s[6:7], s[0:1]
	s_waitcnt lgkmcnt(0)
	s_barrier
	s_movk_i32 s8, 0x400
	v_mov_b64_e32 v[2:3], s[6:7]
	flat_load_dwordx2 v[0:1], v[2:3] offset:240
	flat_load_dwordx2 v[128:129], v[2:3] offset:304
	flat_load_dwordx2 v[130:131], v[2:3] offset:216
	flat_load_dwordx2 v[132:133], v[2:3] offset:200
	s_movk_i32 s6, 0x1600
	s_mov_b32 s100, -1
	s_ashr_i32 s7, s6, 31
	s_lshr_b32 s7, s7, 24
	s_add_i32 s6, s6, s7
	s_ashr_i32 s12, s6, 8
	s_lshl_b32 s6, s12, 7
	v_mov_b32_e32 v14, v254
	s_cmp_ge_i32 s2, s6
	v_readfirstlane_b32 s7, v14
	s_cbranch_scc1 .LBB0_1280
	v_lshlrev_b32_e32 v2, 4, v14
	v_add_u32_e32 v3, 0x2000, v2
	v_ashrrev_i32_e32 v4, 31, v3
	v_lshrrev_b32_e32 v4, 22, v4
	v_add_u32_e32 v4, v3, v4
	v_ashrrev_i32_e32 v4, 10, v4
	v_mul_i32_i24_e32 v5, 0x400, v4
	v_sub_u32_e32 v3, v3, v5
	v_lshrrev_b32_e32 v5, 4, v3
	v_bitop3_b32 v3, v5, v3, 32 bitop3:0x6c
	v_ashrrev_i32_e32 v5, 31, v3
	v_lshrrev_b32_e32 v5, 26, v5
	v_add_u32_e32 v5, v3, v5
	v_lshlrev_b32_e32 v7, 3, v4
	v_ashrrev_i32_e32 v6, 6, v5
	v_and_b32_e32 v7, -16, v7
	v_lshlrev_b32_e32 v4, 5, v4
	v_add_u32_e32 v7, v6, v7
	v_and_b32_e32 v15, 32, v4
	v_and_b32_e32 v4, 0xc0, v5
	v_and_b32_e32 v6, 3, v6
	s_mov_b32 s13, 0x7fffffe0
	v_lshrrev_b32_e32 v8, 2, v7
	v_lshlrev_b32_e32 v9, 1, v7
	v_sub_u32_e32 v3, v3, v4
	v_mov_b32_e32 v4, 1
	v_and_or_b32 v6, v7, s13, v6
	v_and_b32_e32 v8, 4, v8
	v_and_b32_e32 v9, 24, v9
	v_ashrrev_i16_sdwa v3, v4, sext(v3) dst_sel:DWORD dst_unused:UNUSED_PAD src0_sel:DWORD src1_sel:BYTE_0
	v_or3_b32 v6, v6, v8, v9
	v_bfe_i32 v16, v3, 0, 16
	v_mul_lo_u32 v6, v6, s8
	v_add_u32_e32 v3, v15, v16
	v_mul_lo_u32 v17, v7, s8
	v_add_lshl_u32 v134, v6, v3, 1
	v_add_lshl_u32 v136, v3, v17, 1
	v_bfe_i32 v3, v14, 27, 1
	v_lshrrev_b32_e32 v3, 22, v3
	v_add_u32_e32 v3, v2, v3
	v_and_b32_e32 v3, 0xfffffc00, v3
	v_sub_u32_e32 v2, v2, v3
	v_ashrrev_i32_e32 v5, 31, v14
	v_lshrrev_b32_e32 v3, 4, v2
	v_lshrrev_b32_e32 v5, 26, v5
	v_bitop3_b32 v3, v3, v2, 32 bitop3:0x6c
	v_ashrrev_i32_e32 v2, 31, v2
	v_add_u32_e32 v5, v14, v5
	v_lshrrev_b32_e32 v2, 26, v2
	v_ashrrev_i32_e32 v5, 6, v5
	v_add_u32_e32 v2, v3, v2
	v_lshlrev_b32_e32 v6, 3, v5
	v_ashrrev_i32_e32 v2, 6, v2
	v_and_b32_e32 v6, -16, v6
	v_add_u32_e32 v6, v2, v6
	v_and_b32_e32 v7, 3, v2
	v_and_or_b32 v7, v6, s13, v7
	s_lshr_b32 s13, s3, 29
	s_add_i32 s13, s2, s13
	s_ashr_i32 s10, s7, 6
	s_ashr_i32 s9, s8, 31
	s_lshl_b32 s31, s12, 4
	s_ashr_i32 s18, s13, 3
	s_and_b32 s13, s13, -8
	s_ashr_i32 s11, s7, 8
	s_lshl_b64 s[14:15], s[8:9], 8
	s_lshl_b64 s[16:17], s[8:9], 9
	s_lshl_b32 s29, s10, 10
	s_sub_i32 s13, s2, s13
	s_or_b32 s34, s31, 1
	s_cmp_lt_i32 s13, 0
	s_cselect_b32 s19, s34, s31
	s_lshl_b32 s35, s12, 3
	v_mul_i32_i24_e32 v2, 64, v2
	s_abs_i32 s36, s35
	v_sub_u32_e32 v2, v3, v2
	v_cvt_f32_u32_e32 v3, s36
	s_mul_i32 s13, s19, s13
	s_sub_i32 s19, 0, s36
	s_add_i32 s13, s13, s18
	v_rcp_iflag_f32_e32 v3, v3
	s_ashr_i32 s18, s13, 31
	s_bfe_i32 s37, s12, 0x1001c
	s_xor_b32 s12, s18, s37
	v_mul_f32_e32 v3, 0x4f7ffffe, v3
	v_cvt_u32_f32_e32 v3, v3
	s_abs_i32 s18, s13
	v_lshrrev_b32_e32 v8, 2, v6
	v_lshlrev_b32_e32 v9, 1, v6
	v_readfirstlane_b32 s41, v3
	s_mul_i32 s19, s19, s41
	s_mul_hi_u32 s19, s41, s19
	s_add_i32 s41, s41, s19
	s_mul_hi_u32 s19, s18, s41
	s_mul_i32 s20, s19, s36
	s_sub_i32 s18, s18, s20
	s_add_i32 s20, s19, 1
	s_sub_i32 s21, s18, s36
	s_cmp_ge_u32 s18, s36
	s_cselect_b32 s19, s20, s19
	s_cselect_b32 s18, s21, s18
	s_add_i32 s20, s19, 1
	s_cmp_ge_u32 s18, s36
	s_cselect_b32 s18, s20, s19
	s_xor_b32 s18, s18, s12
	s_sub_i32 s12, s18, s12
	s_lshl_b32 s18, s12, 3
	s_sub_i32 s19, 0x80, s18
	s_min_i32 s19, s19, 8
	s_abs_i32 s20, s19
	v_cvt_f32_u32_e32 v3, s20
	v_and_b32_e32 v8, 4, v8
	v_and_b32_e32 v9, 24, v9
	v_lshlrev_b32_e32 v5, 5, v5
	v_ashrrev_i16_sdwa v2, v4, sext(v2) dst_sel:DWORD dst_unused:UNUSED_PAD src0_sel:DWORD src1_sel:BYTE_0
	v_or3_b32 v7, v7, v8, v9
	v_and_b32_e32 v18, 32, v5
	v_bfe_i32 v19, v2, 0, 16
	v_mul_lo_u32 v7, v7, s8
	v_add_u32_e32 v2, v18, v19
	v_mul_lo_u32 v20, v6, s8
	v_add_lshl_u32 v138, v7, v2, 1
	v_add_lshl_u32 v140, v2, v20, 1
	v_rcp_iflag_f32_e32 v2, v3
	s_sub_i32 s22, 0, s20
	s_mul_i32 s12, s12, s35
	s_sub_i32 s12, s13, s12
	v_mul_f32_e32 v2, 0x4f7ffffe, v2
	v_cvt_u32_f32_e32 v2, v2
	s_abs_i32 s21, s12
	s_xor_b32 s13, s12, s19
	s_ashr_i32 s13, s13, 31
	v_readfirstlane_b32 s23, v2
	s_mul_i32 s22, s22, s23
	s_mul_hi_u32 s22, s23, s22
	s_add_i32 s23, s23, s22
	s_mul_hi_u32 s22, s21, s23
	s_mul_i32 s23, s22, s20
	s_sub_i32 s21, s21, s23
	s_add_i32 s23, s22, 1
	s_sub_i32 s24, s21, s20
	s_cmp_ge_u32 s21, s20
	s_cselect_b32 s22, s23, s22
	s_cselect_b32 s21, s24, s21
	s_add_i32 s23, s22, 1
	s_cmp_ge_u32 s21, s20
	s_cselect_b32 s20, s23, s22
	s_xor_b32 s20, s20, s13
	s_sub_i32 s67, s20, s13
	s_mul_i32 s13, s67, s19
	s_sub_i32 s12, s12, s13
	s_add_i32 s12, s12, s18
	s_ashr_i32 s18, s67, 31
	s_mul_i32 s20, s16, s18
	s_lshr_b64 s[18:19], s[8:9], 23
	s_mul_i32 s19, s18, s67
	v_mov_b32_e32 v2, s67
	s_add_i32 s19, s20, s19
	s_waitcnt vmcnt(0) lgkmcnt(0)
	v_mad_u64_u32 v[158:159], s[20:21], s16, v2, v[128:129]
	v_mov_b32_e32 v143, 0
	v_add_u32_e32 v159, s19, v159
	s_add_i32 s46, s29, 0
	v_mov_b32_e32 v139, v143
	s_ashr_i32 s13, s12, 31
	s_add_i32 m0, s46, 0x10000
	v_lshl_add_u64 v[6:7], v[158:159], 0, v[138:139]
	v_mov_b32_e32 v135, v143
	global_load_lds_dwordx4 v[6:7], off
	v_lshl_add_u64 v[8:9], v[158:159], 0, v[134:135]
	s_add_i32 m0, s46, 0x12000
	v_lshl_add_u64 v[4:5], v[158:159], 0, s[14:15]
	s_mul_i32 s13, s16, s13
	s_mul_i32 s18, s18, s12
	v_mov_b32_e32 v10, s12
	global_load_lds_dwordx4 v[8:9], off
	s_add_i32 m0, s46, 0x14000
	v_lshl_add_u64 v[2:3], v[4:5], 0, v[138:139]
	s_add_i32 s13, s13, s18
	v_mad_u64_u32 v[160:161], s[18:19], s16, v10, v[132:133]
	global_load_lds_dwordx4 v[2:3], off
	v_lshl_add_u64 v[4:5], v[4:5], 0, v[134:135]
	s_add_i32 m0, s46, 0x16000
	v_add_u32_e32 v161, s13, v161
	v_mov_b32_e32 v141, v143
	global_load_lds_dwordx4 v[4:5], off
	v_lshl_add_u64 v[10:11], v[160:161], 0, v[140:141]
	s_mov_b32 m0, s46
	v_mov_b32_e32 v137, v143
	s_add_i32 s47, s46, 0x2000
	global_load_lds_dwordx4 v[10:11], off
	v_lshl_add_u64 v[12:13], v[160:161], 0, v[136:137]
	s_mov_b32 m0, s47
	v_lshl_add_u64 v[22:23], v[160:161], 0, s[14:15]
	s_add_i32 s48, s46, 0x4000
	global_load_lds_dwordx4 v[12:13], off
	v_lshl_add_u64 v[24:25], v[22:23], 0, v[140:141]
	s_mov_b32 m0, s48
	s_add_i32 s49, s46, 0x6000
	global_load_lds_dwordx4 v[24:25], off
	v_lshl_add_u64 v[22:23], v[22:23], 0, v[136:137]
	s_mov_b32 m0, s49
	s_cmp_eq_u32 s11, 1
	global_load_lds_dwordx4 v[22:23], off
	s_cselect_b64 s[18:19], -1, 0
	s_cmp_lg_u32 s11, 1
	s_mov_b32 s21, 0
	s_cbranch_scc1 .LBB0_1262
	s_barrier

; __device__ __forceinline__ int tid_fresh() { int t = threadIdx.x; asm volatile("" : "+v"(t)); return t; }
; #define PG8_BAR __builtin_amdgcn_s_barrier()
; template <class Epi, class Sched, bool ALIGN_EPI = false, bool SP2 = false>
; __device__ __forceinline__ void gemm_phase(PG8_LAS unsigned char* lds, const Gemm g, const Sched& S, const Epi& E) {
;     const int tid = tid_fresh(), wid = __builtin_amdgcn_readfirstlane(tid >> 6), lane = tid & 63, wr = wid >> 2, wc = wid & 3, fr = lane & 15, fq = lane >> 4;
;     const int K = g.K, nt = K / BK;
;     unsigned voffA[2], voffB[2];
; #pragma unroll
;     for (int i = 0; i < 2; ++i) { int R, C; stage_rc(tid * 16 + i * 8192, R, C); const int Rb = Epi::PERM ? ((R & ~31) + perm32(R & 31)) : R;
;         voffA[i] = (unsigned)(R * K + C) * 2u; voffB[i] = (unsigned)(Rb * K + C) * 2u; }
;     const size_t kstep = (size_t)(BK * 2);
;     const size_t hstep = (size_t)HALF * K * 2;
;     const size_t tstep = 2 * hstep;
;     const unsigned ldsw = (unsigned)wid * 1024u;
;     const int aoff = lds_byte(wr * 64 + fr, fq * 8), boff = lds_byte(wc * 32 + fr, fq * 8);
;     ...
;     Unit cur, nxt; int ui = 0;
;     if (!S.next(0, cur)) return;
;     f32x4 acc[2][2][4][2];
; #pragma unroll
;     for (int a = 0; a < 2; ++a)
; #pragma unroll
;         for (int b = 0; b < 2; ++b)
; #pragma unroll
;             for (int m = 0; m < 4; ++m)
; #pragma unroll
;                 for (int n = 0; n < 2; ++n) acc[a][b][m][n] = (f32x4){0.f, 0.f, 0.f, 0.f};
;     bf16x8 At[4][2], B0[2][2], B1[2][2];
;     const char* cA = (const char*)g.A + (size_t)cur.pm * tstep; const char* cB = (const char*)g.Bt + (size_t)cur.pn * tstep;
;     S.a_ready(cur);
;     if constexpr (SP2) {
;         PG8_STAGE(PG8_SB(0, 0), cB, voffB); PG8_STAGE(PG8_SB(0, 1), cB + hstep, voffB); PG8_STAGE(PG8_SA(0, 0), cA, voffA); PG8_STAGE(PG8_SA(0, 1), cA + hstep, voffA);
;         if (wr == 1) PG8_BAR;
;         PG8_WAIT_V(2); PG8_BAR;
;         PG8_STAGE(PG8_SB(1, 0), cB + kstep, voffB); PG8_STAGE(PG8_SA(1, 0), cA + kstep, voffA); PG8_STAGE(PG8_SB(1, 1), cB + hstep + kstep, voffB);
;         PG8_WAIT_V(6); PG8_BAR;
;     } else {
;         PG8_STAGE(PG8_SB(0, 0), cB, voffB); PG8_STAGE(PG8_SA(0, 0), cA, voffA); PG8_STAGE(PG8_SB(0, 1), cB + hstep, voffB); PG8_STAGE(PG8_SA(0, 1), cA + hstep, voffA);
;         if (wr == 1) PG8_BAR;
;         PG8_WAIT_V(4); PG8_BAR;
.LBB0_1762:
	s_or_b64 exec, exec, s[46:47]
	s_mov_b64 s[6:7], s[0:1]
	s_waitcnt lgkmcnt(0)
	s_barrier
	s_movk_i32 s8, 0x400
	v_mov_b64_e32 v[2:3], s[6:7]
	flat_load_dwordx2 v[0:1], v[2:3] offset:232
	flat_load_dwordx2 v[128:129], v[2:3] offset:320
	flat_load_dwordx2 v[130:131], v[2:3] offset:216
	flat_load_dwordx2 v[132:133], v[2:3] offset:192
	s_movk_i32 s6, 0x1600
	s_mov_b32 s100, -1
	s_ashr_i32 s7, s6, 31
	s_lshr_b32 s7, s7, 24
	s_add_i32 s6, s6, s7
	s_ashr_i32 s12, s6, 8
	s_lshl_b32 s6, s12, 7
	v_mov_b32_e32 v14, v254
	s_cmp_ge_i32 s2, s6
	v_readfirstlane_b32 s7, v14
	s_cbranch_scc1 .LBB0_1783
	v_lshlrev_b32_e32 v2, 4, v14
	v_add_u32_e32 v3, 0x2000, v2
	v_ashrrev_i32_e32 v4, 31, v3
	v_lshrrev_b32_e32 v4, 22, v4
	v_add_u32_e32 v4, v3, v4
	v_ashrrev_i32_e32 v4, 10, v4
	v_mul_i32_i24_e32 v5, 0x400, v4
	v_sub_u32_e32 v3, v3, v5
	v_lshrrev_b32_e32 v5, 4, v3
	v_bitop3_b32 v3, v5, v3, 32 bitop3:0x6c
	v_ashrrev_i32_e32 v5, 31, v3
	v_lshrrev_b32_e32 v5, 26, v5
	v_add_u32_e32 v5, v3, v5
	v_lshlrev_b32_e32 v7, 3, v4
	v_ashrrev_i32_e32 v6, 6, v5
	v_and_b32_e32 v7, -16, v7
	v_lshlrev_b32_e32 v4, 5, v4
	v_add_u32_e32 v7, v6, v7
	v_and_b32_e32 v15, 32, v4
	v_and_b32_e32 v4, 0xc0, v5
	v_and_b32_e32 v6, 3, v6
	s_mov_b32 s13, 0x7fffffe0
	v_lshrrev_b32_e32 v8, 2, v7
	v_lshlrev_b32_e32 v9, 1, v7
	v_sub_u32_e32 v3, v3, v4
	v_mov_b32_e32 v4, 1
	v_and_or_b32 v6, v7, s13, v6
	v_and_b32_e32 v8, 4, v8
	v_and_b32_e32 v9, 24, v9
	v_ashrrev_i16_sdwa v3, v4, sext(v3) dst_sel:DWORD dst_unused:UNUSED_PAD src0_sel:DWORD src1_sel:BYTE_0
	v_or3_b32 v6, v6, v8, v9
	v_bfe_i32 v16, v3, 0, 16
	v_mul_lo_u32 v6, v6, s8
	v_add_u32_e32 v3, v15, v16
	v_mul_lo_u32 v17, v7, s8
	v_add_lshl_u32 v134, v6, v3, 1
	v_add_lshl_u32 v136, v3, v17, 1
	v_bfe_i32 v3, v14, 27, 1
	v_lshrrev_b32_e32 v3, 22, v3
	v_add_u32_e32 v3, v2, v3
	v_and_b32_e32 v3, 0xfffffc00, v3
	v_sub_u32_e32 v2, v2, v3
	v_ashrrev_i32_e32 v5, 31, v14
	v_lshrrev_b32_e32 v3, 4, v2
	v_lshrrev_b32_e32 v5, 26, v5
	v_bitop3_b32 v3, v3, v2, 32 bitop3:0x6c
	v_ashrrev_i32_e32 v2, 31, v2
	v_add_u32_e32 v5, v14, v5
	v_lshrrev_b32_e32 v2, 26, v2
	v_ashrrev_i32_e32 v5, 6, v5
	v_add_u32_e32 v2, v3, v2
	v_lshlrev_b32_e32 v6, 3, v5
	v_ashrrev_i32_e32 v2, 6, v2
	v_and_b32_e32 v6, -16, v6
	v_add_u32_e32 v6, v2, v6
	v_and_b32_e32 v7, 3, v2
	v_and_or_b32 v7, v6, s13, v7
	s_lshr_b32 s13, s3, 29
	s_add_i32 s13, s2, s13
	s_ashr_i32 s10, s7, 6
	s_ashr_i32 s9, s8, 31
	s_lshl_b32 s31, s12, 4
	s_ashr_i32 s18, s13, 3
	s_and_b32 s13, s13, -8
	s_ashr_i32 s11, s7, 8
	s_lshl_b64 s[14:15], s[8:9], 8
	s_lshl_b64 s[16:17], s[8:9], 9
	s_lshl_b32 s29, s10, 10
	s_sub_i32 s13, s2, s13
	s_or_b32 s34, s31, 1
	s_cmp_lt_i32 s13, 0
	s_cselect_b32 s19, s34, s31
	s_lshl_b32 s35, s12, 3
	v_mul_i32_i24_e32 v2, 64, v2
	s_abs_i32 s36, s35
	v_sub_u32_e32 v2, v3, v2
	v_cvt_f32_u32_e32 v3, s36
	s_mul_i32 s13, s19, s13
	s_sub_i32 s19, 0, s36
	s_add_i32 s13, s13, s18
	v_rcp_iflag_f32_e32 v3, v3
	s_ashr_i32 s18, s13, 31
	s_bfe_i32 s37, s12, 0x1001c
	s_xor_b32 s12, s18, s37
	v_mul_f32_e32 v3, 0x4f7ffffe, v3
	v_cvt_u32_f32_e32 v3, v3
	s_abs_i32 s18, s13
	v_lshrrev_b32_e32 v8, 2, v6
	v_lshlrev_b32_e32 v9, 1, v6
	v_readfirstlane_b32 s41, v3
	s_mul_i32 s19, s19, s41
	s_mul_hi_u32 s19, s41, s19
	s_add_i32 s41, s41, s19
	s_mul_hi_u32 s19, s18, s41
	s_mul_i32 s20, s19, s36
	s_sub_i32 s18, s18, s20
	s_add_i32 s20, s19, 1
	s_sub_i32 s21, s18, s36
	s_cmp_ge_u32 s18, s36
	s_cselect_b32 s19, s20, s19
	s_cselect_b32 s18, s21, s18
	s_add_i32 s20, s19, 1
	s_cmp_ge_u32 s18, s36
	s_cselect_b32 s18, s20, s19
	s_xor_b32 s18, s18, s12
	s_sub_i32 s12, s18, s12
	s_lshl_b32 s18, s12, 3
	s_sub_i32 s19, 0x80, s18
	s_min_i32 s19, s19, 8
	s_abs_i32 s20, s19
	v_cvt_f32_u32_e32 v3, s20
	v_and_b32_e32 v8, 4, v8
	v_and_b32_e32 v9, 24, v9
	v_lshlrev_b32_e32 v5, 5, v5
	v_ashrrev_i16_sdwa v2, v4, sext(v2) dst_sel:DWORD dst_unused:UNUSED_PAD src0_sel:DWORD src1_sel:BYTE_0
	v_or3_b32 v7, v7, v8, v9
	v_and_b32_e32 v18, 32, v5
	v_bfe_i32 v19, v2, 0, 16
	v_mul_lo_u32 v7, v7, s8
	v_add_u32_e32 v2, v18, v19
	v_mul_lo_u32 v20, v6, s8
	v_add_lshl_u32 v138, v7, v2, 1
	v_add_lshl_u32 v140, v2, v20, 1
	v_rcp_iflag_f32_e32 v2, v3
	s_sub_i32 s22, 0, s20
	s_mul_i32 s12, s12, s35
	s_sub_i32 s12, s13, s12
	v_mul_f32_e32 v2, 0x4f7ffffe, v2
	v_cvt_u32_f32_e32 v2, v2
	s_abs_i32 s21, s12
	s_xor_b32 s13, s12, s19
	s_ashr_i32 s13, s13, 31
	v_readfirstlane_b32 s23, v2
	s_mul_i32 s22, s22, s23
	s_mul_hi_u32 s22, s23, s22
	s_add_i32 s23, s23, s22
	s_mul_hi_u32 s22, s21, s23
	s_mul_i32 s23, s22, s20
	s_sub_i32 s21, s21, s23
	s_add_i32 s23, s22, 1
	s_sub_i32 s24, s21, s20
	s_cmp_ge_u32 s21, s20
	s_cselect_b32 s22, s23, s22
	s_cselect_b32 s21, s24, s21
	s_add_i32 s23, s22, 1
	s_cmp_ge_u32 s21, s20
	s_cselect_b32 s20, s23, s22
	s_xor_b32 s20, s20, s13
	s_sub_i32 s66, s20, s13
	s_mul_i32 s13, s66, s19
	s_sub_i32 s12, s12, s13
	s_add_i32 s12, s12, s18
	s_ashr_i32 s18, s66, 31
	s_mul_i32 s20, s16, s18
	s_lshr_b64 s[18:19], s[8:9], 23
	s_mul_i32 s19, s18, s66
	v_mov_b32_e32 v2, s66
	s_add_i32 s19, s20, s19
	s_waitcnt vmcnt(0) lgkmcnt(0)
	v_mad_u64_u32 v[158:159], s[20:21], s16, v2, v[128:129]
	v_mov_b32_e32 v143, 0
	v_add_u32_e32 v159, s19, v159
	s_add_i32 s46, s29, 0
	v_mov_b32_e32 v139, v143
	s_ashr_i32 s13, s12, 31
	s_add_i32 m0, s46, 0x10000
	v_lshl_add_u64 v[6:7], v[158:159], 0, v[138:139]
	v_mov_b32_e32 v135, v143
	global_load_lds_dwordx4 v[6:7], off
	v_lshl_add_u64 v[8:9], v[158:159], 0, v[134:135]
	s_add_i32 m0, s46, 0x12000
	v_lshl_add_u64 v[4:5], v[158:159], 0, s[14:15]
	s_mul_i32 s13, s16, s13
	s_mul_i32 s18, s18, s12
	v_mov_b32_e32 v10, s12
	global_load_lds_dwordx4 v[8:9], off
	s_add_i32 m0, s46, 0x14000
	v_lshl_add_u64 v[2:3], v[4:5], 0, v[138:139]
	s_add_i32 s13, s13, s18
	v_mad_u64_u32 v[160:161], s[18:19], s16, v10, v[132:133]
	global_load_lds_dwordx4 v[2:3], off
	v_lshl_add_u64 v[4:5], v[4:5], 0, v[134:135]
	s_add_i32 m0, s46, 0x16000
	v_add_u32_e32 v161, s13, v161
	v_mov_b32_e32 v141, v143
	global_load_lds_dwordx4 v[4:5], off
	v_lshl_add_u64 v[10:11], v[160:161], 0, v[140:141]
	s_mov_b32 m0, s46
	v_mov_b32_e32 v137, v143
	s_add_i32 s47, s46, 0x2000
	global_load_lds_dwordx4 v[10:11], off
	v_lshl_add_u64 v[12:13], v[160:161], 0, v[136:137]
	s_mov_b32 m0, s47
	v_lshl_add_u64 v[22:23], v[160:161], 0, s[14:15]
	s_add_i32 s48, s46, 0x4000
	global_load_lds_dwordx4 v[12:13], off
	v_lshl_add_u64 v[24:25], v[22:23], 0, v[140:141]
	s_mov_b32 m0, s48
	s_add_i32 s49, s46, 0x6000
	global_load_lds_dwordx4 v[24:25], off
	v_lshl_add_u64 v[22:23], v[22:23], 0, v[136:137]
	s_mov_b32 m0, s49
	s_cmp_eq_u32 s11, 1
	global_load_lds_dwordx4 v[22:23], off
	s_cselect_b64 s[18:19], -1, 0
	s_cmp_lg_u32 s11, 1
	s_mov_b32 s21, 0
	s_cbranch_scc1 .LBB0_1765
	s_barrier

; #define LAS __attribute__((address_space(3)))
; __global__ void __launch_bounds__(NTHREADS, 2) k_mega(Params Pdummy) {
;   extern __shared__ __attribute__((aligned(16))) unsigned char lds_dyn[];
;   unsigned char* smem = lds_dyn;
;   LAS unsigned char* lds = (LAS unsigned char*)lds_dyn;
	.amdhsa_kernel _Z6k_mega6Params
		.amdhsa_group_segment_fixed_size 16384
		.amdhsa_private_segment_fixed_size 0
		.amdhsa_kernarg_size 800
		.amdhsa_user_sgpr_count 2
		.amdhsa_user_sgpr_dispatch_ptr 0
		.amdhsa_user_sgpr_queue_ptr 0
		.amdhsa_user_sgpr_kernarg_segment_ptr 1
		.amdhsa_user_sgpr_dispatch_id 0
		.amdhsa_user_sgpr_kernarg_preload_length 0
		.amdhsa_user_sgpr_kernarg_preload_offset 0
		.amdhsa_user_sgpr_private_segment_size 0
		.amdhsa_uses_dynamic_stack 0
		.amdhsa_enable_private_segment 0
		.amdhsa_system_sgpr_workgroup_id_x 1
		.amdhsa_system_sgpr_workgroup_id_y 0
		.amdhsa_system_sgpr_workgroup_id_z 0
		.amdhsa_system_sgpr_workgroup_info 0
		.amdhsa_system_vgpr_workitem_id 2
		.amdhsa_next_free_vgpr 256
		.amdhsa_next_free_sgpr 102
		.amdhsa_accum_offset 256
		.amdhsa_reserve_vcc 1
		.amdhsa_float_round_mode_32 0
		.amdhsa_float_round_mode_16_64 0
		.amdhsa_float_denorm_mode_32 3
		.amdhsa_float_denorm_mode_16_64 3
		.amdhsa_dx10_clamp 1
		.amdhsa_ieee_mode 1
		.amdhsa_fp16_overflow 0
		.amdhsa_tg_split 0
		.amdhsa_exception_fp_ieee_invalid_op 0
		.amdhsa_exception_fp_denorm_src 0
		.amdhsa_exception_fp_ieee_div_zero 0
		.amdhsa_exception_fp_ieee_overflow 0
		.amdhsa_exception_fp_ieee_underflow 0
		.amdhsa_exception_fp_ieee_inexact 0
		.amdhsa_exception_int_div_zero 0
	.end_amdhsa_kernel

; #define LAS __attribute__((address_space(3)))
; __global__ void __launch_bounds__(NTHREADS, 2) k_mega(Params Pdummy) {
;   extern __shared__ __attribute__((aligned(16))) unsigned char lds_dyn[];
;   unsigned char* smem = lds_dyn;
;   LAS unsigned char* lds = (LAS unsigned char*)lds_dyn;
amdhsa.kernels:
  - .agpr_count:     0
    .args:
      - .offset:         0
        .size:           544
        .value_kind:     by_value
      - .offset:         544
        .size:           4
        .value_kind:     hidden_block_count_x
      - .offset:         548
        .size:           4
        .value_kind:     hidden_block_count_y
      - .offset:         552
        .size:           4
        .value_kind:     hidden_block_count_z
      - .offset:         556
        .size:           2
        .value_kind:     hidden_group_size_x
      - .offset:         558
        .size:           2
        .value_kind:     hidden_group_size_y
      - .offset:         560
        .size:           2
        .value_kind:     hidden_group_size_z
      - .offset:         562
        .size:           2
        .value_kind:     hidden_remainder_x
      - .offset:         564
        .size:           2
        .value_kind:     hidden_remainder_y
      - .offset:         566
        .size:           2
        .value_kind:     hidden_remainder_z
      - .offset:         584
        .size:           8
        .value_kind:     hidden_global_offset_x
      - .offset:         592
        .size:           8
        .value_kind:     hidden_global_offset_y
      - .offset:         600
        .size:           8
        .value_kind:     hidden_global_offset_z
      - .offset:         608
        .size:           2
        .value_kind:     hidden_grid_dims
      - .offset:         632
        .size:           8
        .value_kind:     hidden_multigrid_sync_arg
      - .offset:         664
        .size:           4
        .value_kind:     hidden_dynamic_lds_size
    .group_segment_fixed_size: 16384
    .kernarg_segment_align: 8
    .kernarg_segment_size: 800
    .language:       OpenCL C
    .language_version:
      - 2
      - 0
    .max_flat_workgroup_size: 512
    .name:           _Z6k_mega6Params
    .private_segment_fixed_size: 0
    .sgpr_count:     108
    .sgpr_spill_count: 2
    .symbol:         _Z6k_mega6Params.kd
    .uniform_work_group_size: 1
    .uses_dynamic_stack: false
    .vgpr_count:     256
    .vgpr_spill_count: 0
    .wavefront_size: 64
